# strategy 7.11: loop-back SALU block (counter, pointer bumps, exit test) moved in front of the K-loop's closing s_barrier in all six GEMM mainloops
# baseline (speedup 1.0000x reference)
.LBB0_504:
	ds_read_b128 v[144:147], v153
	ds_read_b128 v[158:161], v153 offset:1024
	ds_read_b128 v[162:165], v153 offset:2048
	ds_read_b128 v[166:169], v153 offset:3072
	ds_read_b128 v[170:173], v154
	ds_read_b128 v[174:177], v154 offset:1024
	ds_read_b128 v[178:181], v154 offset:2048
	ds_read_b128 v[184:187], v154 offset:3072
	s_add_u32 s22, s20, 0xfff80080
	s_addc_u32 s23, s21, -1
	s_cmp_eq_u32 s46, 28
	s_cselect_b32 s25, s13, s23
	s_cselect_b32 s24, s42, s22
	s_cselect_b32 s23, s3, s45
	s_cselect_b32 s22, s43, s44
	v_lshl_add_u64 v[148:149], s[20:21], 0, v[136:137]
	s_add_i32 m0, s28, 0xc000
	ds_read_b128 v[190:193], v155
	ds_read_b128 v[194:197], v155 offset:1024
	ds_read_b128 v[198:201], v155 offset:2048
	ds_read_b128 v[202:205], v155 offset:3072
	ds_read_b128 v[206:209], v155 offset:4096
	ds_read_b128 v[210:213], v155 offset:5120
	ds_read_b128 v[214:217], v155 offset:6144
	ds_read_b128 v[218:221], v155 offset:7168
	global_load_lds_dwordx4 v[148:149], off
	v_lshl_add_u64 v[148:149], s[20:21], 0, v[138:139]
	s_add_i32 m0, s28, 0xe000
	s_nop 0
	global_load_lds_dwordx4 v[148:149], off
	s_waitcnt vmcnt(8)
	s_waitcnt lgkmcnt(0)
	s_barrier
	s_setprio 1
	s_waitcnt lgkmcnt(0)
	v_mfma_f32_16x16x32_bf16 v[124:127], v[144:147], v[190:193], v[124:127]
	v_mfma_f32_16x16x32_bf16 v[116:119], v[162:165], v[190:193], v[116:119]
	v_mfma_f32_16x16x32_bf16 v[108:111], v[144:147], v[198:201], v[108:111]
	v_mfma_f32_16x16x32_bf16 v[100:103], v[162:165], v[198:201], v[100:103]
	v_mfma_f32_16x16x32_bf16 v[92:95], v[144:147], v[206:209], v[92:95]
	v_mfma_f32_16x16x32_bf16 v[84:87], v[162:165], v[206:209], v[84:87]
	v_mfma_f32_16x16x32_bf16 v[76:79], v[144:147], v[214:217], v[76:79]
	v_mfma_f32_16x16x32_bf16 v[68:71], v[162:165], v[214:217], v[68:71]
	v_mfma_f32_16x16x32_bf16 v[124:127], v[158:161], v[194:197], v[124:127]
	v_mfma_f32_16x16x32_bf16 v[116:119], v[166:169], v[194:197], v[116:119]
	v_mfma_f32_16x16x32_bf16 v[108:111], v[158:161], v[202:205], v[108:111]
	v_mfma_f32_16x16x32_bf16 v[100:103], v[166:169], v[202:205], v[100:103]
	v_mfma_f32_16x16x32_bf16 v[92:95], v[158:161], v[210:213], v[92:95]
	v_mfma_f32_16x16x32_bf16 v[84:87], v[166:169], v[210:213], v[84:87]
	v_mfma_f32_16x16x32_bf16 v[76:79], v[158:161], v[218:221], v[76:79]
	v_mfma_f32_16x16x32_bf16 v[68:71], v[166:169], v[218:221], v[68:71]
	s_setprio 0
	s_setprio 1
	v_mfma_f32_16x16x32_bf16 v[120:123], v[170:173], v[190:193], v[120:123]
	v_mfma_f32_16x16x32_bf16 v[112:115], v[178:181], v[190:193], v[112:115]
	v_mfma_f32_16x16x32_bf16 v[104:107], v[170:173], v[198:201], v[104:107]
	v_mfma_f32_16x16x32_bf16 v[96:99], v[178:181], v[198:201], v[96:99]
	v_mfma_f32_16x16x32_bf16 v[88:91], v[170:173], v[206:209], v[88:91]
	v_mfma_f32_16x16x32_bf16 v[80:83], v[178:181], v[206:209], v[80:83]
	v_mfma_f32_16x16x32_bf16 v[72:75], v[170:173], v[214:217], v[72:75]
	v_mfma_f32_16x16x32_bf16 v[64:67], v[178:181], v[214:217], v[64:67]
	v_mfma_f32_16x16x32_bf16 v[120:123], v[174:177], v[194:197], v[120:123]
	v_mfma_f32_16x16x32_bf16 v[112:115], v[184:187], v[194:197], v[112:115]
	v_mfma_f32_16x16x32_bf16 v[104:107], v[174:177], v[202:205], v[104:107]
	v_mfma_f32_16x16x32_bf16 v[96:99], v[184:187], v[202:205], v[96:99]
	v_mfma_f32_16x16x32_bf16 v[88:91], v[174:177], v[210:213], v[88:91]
	v_mfma_f32_16x16x32_bf16 v[80:83], v[184:187], v[210:213], v[80:83]
	v_mfma_f32_16x16x32_bf16 v[72:75], v[174:177], v[218:221], v[72:75]
	v_mfma_f32_16x16x32_bf16 v[64:67], v[184:187], v[218:221], v[64:67]
	s_setprio 0
	s_barrier
	s_add_i32 s47, s38, s27
	v_lshl_add_u64 v[148:149], s[22:23], 0, v[130:131]
	s_mov_b32 m0, s47
	ds_read_b128 v[190:193], v155 offset:16384
	ds_read_b128 v[194:197], v155 offset:17408
	ds_read_b128 v[198:201], v155 offset:18432
	ds_read_b128 v[202:205], v155 offset:19456
	ds_read_b128 v[206:209], v155 offset:20480
	ds_read_b128 v[210:213], v155 offset:21504
	ds_read_b128 v[214:217], v155 offset:22528
	ds_read_b128 v[218:221], v155 offset:23552
	global_load_lds_dwordx4 v[148:149], off
	s_add_i32 m0, s47, 0x2000
	s_add_u32 s48, s22, 0x80000
	v_lshl_add_u64 v[222:223], s[22:23], 0, v[134:135]
	s_addc_u32 s49, s23, 0
	s_add_i32 s47, s39, s27
	global_load_lds_dwordx4 v[222:223], off
	v_lshl_add_u64 v[224:225], s[48:49], 0, v[130:131]
	s_mov_b32 m0, s47
	v_lshl_add_u64 v[226:227], s[24:25], 0, v[132:133]
	global_load_lds_dwordx4 v[224:225], off
	v_lshl_add_u64 v[224:225], s[48:49], 0, v[134:135]
	s_add_i32 m0, s47, 0x2000
	s_nop 0
	global_load_lds_dwordx4 v[224:225], off
	v_lshl_add_u64 v[224:225], s[24:25], 0, v[128:129]
	s_mov_b32 m0, s28
	s_nop 0
	global_load_lds_dwordx4 v[224:225], off
	s_mov_b32 m0, s29
	s_nop 0
	global_load_lds_dwordx4 v[226:227], off
	s_waitcnt vmcnt(8)
	s_waitcnt lgkmcnt(0)
	s_barrier
	s_setprio 1
	s_waitcnt lgkmcnt(0)
	v_mfma_f32_16x16x32_bf16 v[60:63], v[144:147], v[190:193], v[60:63]
	v_mfma_f32_16x16x32_bf16 v[52:55], v[162:165], v[190:193], v[52:55]
	v_mfma_f32_16x16x32_bf16 v[44:47], v[144:147], v[198:201], v[44:47]
	v_mfma_f32_16x16x32_bf16 v[36:39], v[162:165], v[198:201], v[36:39]
	v_mfma_f32_16x16x32_bf16 v[28:31], v[144:147], v[206:209], v[28:31]
	v_mfma_f32_16x16x32_bf16 v[20:23], v[162:165], v[206:209], v[20:23]
	v_mfma_f32_16x16x32_bf16 v[12:15], v[144:147], v[214:217], v[12:15]
	v_mfma_f32_16x16x32_bf16 v[4:7], v[162:165], v[214:217], v[4:7]
	v_mfma_f32_16x16x32_bf16 v[60:63], v[158:161], v[194:197], v[60:63]
	v_mfma_f32_16x16x32_bf16 v[52:55], v[166:169], v[194:197], v[52:55]
	v_mfma_f32_16x16x32_bf16 v[44:47], v[158:161], v[202:205], v[44:47]
	v_mfma_f32_16x16x32_bf16 v[36:39], v[166:169], v[202:205], v[36:39]
	v_mfma_f32_16x16x32_bf16 v[28:31], v[158:161], v[210:213], v[28:31]
	v_mfma_f32_16x16x32_bf16 v[20:23], v[166:169], v[210:213], v[20:23]
	v_mfma_f32_16x16x32_bf16 v[12:15], v[158:161], v[218:221], v[12:15]
	v_mfma_f32_16x16x32_bf16 v[4:7], v[166:169], v[218:221], v[4:7]
	s_setprio 0
	s_setprio 1
	v_mfma_f32_16x16x32_bf16 v[56:59], v[170:173], v[190:193], v[56:59]
	v_mfma_f32_16x16x32_bf16 v[48:51], v[178:181], v[190:193], v[48:51]
	v_mfma_f32_16x16x32_bf16 v[40:43], v[170:173], v[198:201], v[40:43]
	v_mfma_f32_16x16x32_bf16 v[32:35], v[178:181], v[198:201], v[32:35]
	v_mfma_f32_16x16x32_bf16 v[24:27], v[170:173], v[206:209], v[24:27]
	v_mfma_f32_16x16x32_bf16 v[16:19], v[178:181], v[206:209], v[16:19]
	v_mfma_f32_16x16x32_bf16 v[8:11], v[170:173], v[214:217], v[8:11]
	v_mfma_f32_16x16x32_bf16 v[0:3], v[178:181], v[214:217], v[0:3]
	v_mfma_f32_16x16x32_bf16 v[56:59], v[174:177], v[194:197], v[56:59]
	v_mfma_f32_16x16x32_bf16 v[48:51], v[184:187], v[194:197], v[48:51]
	v_mfma_f32_16x16x32_bf16 v[40:43], v[174:177], v[202:205], v[40:43]
	v_mfma_f32_16x16x32_bf16 v[32:35], v[184:187], v[202:205], v[32:35]
	v_mfma_f32_16x16x32_bf16 v[24:27], v[174:177], v[210:213], v[24:27]
	v_mfma_f32_16x16x32_bf16 v[16:19], v[184:187], v[210:213], v[16:19]
	v_mfma_f32_16x16x32_bf16 v[8:11], v[174:177], v[218:221], v[8:11]
	v_mfma_f32_16x16x32_bf16 v[0:3], v[184:187], v[218:221], v[0:3]
	s_setprio 0
	s_barrier
	s_add_i32 s47, 0, 0x18000
	v_add_u32_e32 v157, s47, v151
	s_add_i32 s48, 0, 0x1c000
	ds_read_b128 v[144:147], v157
	ds_read_b128 v[158:161], v157 offset:1024
	ds_read_b128 v[162:165], v157 offset:2048
	ds_read_b128 v[166:169], v157 offset:3072
	v_add_u32_e32 v157, s48, v151
	ds_read_b128 v[170:173], v157
	ds_read_b128 v[174:177], v157 offset:1024
	ds_read_b128 v[178:181], v157 offset:2048
	ds_read_b128 v[184:187], v157 offset:3072
	s_add_u32 s24, s24, 0x80000
	s_addc_u32 s25, s25, 0
	s_mov_b32 m0, s30
	v_lshl_add_u64 v[228:229], s[24:25], 0, v[128:129]
	ds_read_b128 v[190:193], v155 offset:32768
	ds_read_b128 v[194:197], v155 offset:33792
	ds_read_b128 v[198:201], v155 offset:34816
	ds_read_b128 v[202:205], v155 offset:35840
	ds_read_b128 v[206:209], v155 offset:36864
	ds_read_b128 v[210:213], v155 offset:37888
	ds_read_b128 v[214:217], v155 offset:38912
	ds_read_b128 v[218:221], v155 offset:39936
	global_load_lds_dwordx4 v[228:229], off
	v_lshl_add_u64 v[228:229], s[24:25], 0, v[132:133]
	s_mov_b32 m0, s31
	s_nop 0
	global_load_lds_dwordx4 v[228:229], off
	s_waitcnt vmcnt(8)
	s_waitcnt lgkmcnt(0)
	s_barrier
	s_setprio 1
	s_waitcnt lgkmcnt(0)
	v_mfma_f32_16x16x32_bf16 v[124:127], v[144:147], v[190:193], v[124:127]
	v_mfma_f32_16x16x32_bf16 v[116:119], v[162:165], v[190:193], v[116:119]
	v_mfma_f32_16x16x32_bf16 v[108:111], v[144:147], v[198:201], v[108:111]
	v_mfma_f32_16x16x32_bf16 v[100:103], v[162:165], v[198:201], v[100:103]
	v_mfma_f32_16x16x32_bf16 v[92:95], v[144:147], v[206:209], v[92:95]
	v_mfma_f32_16x16x32_bf16 v[84:87], v[162:165], v[206:209], v[84:87]
	v_mfma_f32_16x16x32_bf16 v[76:79], v[144:147], v[214:217], v[76:79]
	v_mfma_f32_16x16x32_bf16 v[68:71], v[162:165], v[214:217], v[68:71]
	v_mfma_f32_16x16x32_bf16 v[124:127], v[158:161], v[194:197], v[124:127]
	v_mfma_f32_16x16x32_bf16 v[116:119], v[166:169], v[194:197], v[116:119]
	v_mfma_f32_16x16x32_bf16 v[108:111], v[158:161], v[202:205], v[108:111]
	v_mfma_f32_16x16x32_bf16 v[100:103], v[166:169], v[202:205], v[100:103]
	v_mfma_f32_16x16x32_bf16 v[92:95], v[158:161], v[210:213], v[92:95]
	v_mfma_f32_16x16x32_bf16 v[84:87], v[166:169], v[210:213], v[84:87]
	v_mfma_f32_16x16x32_bf16 v[76:79], v[158:161], v[218:221], v[76:79]
	v_mfma_f32_16x16x32_bf16 v[68:71], v[166:169], v[218:221], v[68:71]
	s_setprio 0
	s_setprio 1
	v_mfma_f32_16x16x32_bf16 v[120:123], v[170:173], v[190:193], v[120:123]
	v_mfma_f32_16x16x32_bf16 v[112:115], v[178:181], v[190:193], v[112:115]
	v_mfma_f32_16x16x32_bf16 v[104:107], v[170:173], v[198:201], v[104:107]
	v_mfma_f32_16x16x32_bf16 v[96:99], v[178:181], v[198:201], v[96:99]
	v_mfma_f32_16x16x32_bf16 v[88:91], v[170:173], v[206:209], v[88:91]
	v_mfma_f32_16x16x32_bf16 v[80:83], v[178:181], v[206:209], v[80:83]
	v_mfma_f32_16x16x32_bf16 v[72:75], v[170:173], v[214:217], v[72:75]
	v_mfma_f32_16x16x32_bf16 v[64:67], v[178:181], v[214:217], v[64:67]
	v_mfma_f32_16x16x32_bf16 v[120:123], v[174:177], v[194:197], v[120:123]
	v_mfma_f32_16x16x32_bf16 v[112:115], v[184:187], v[194:197], v[112:115]
	v_mfma_f32_16x16x32_bf16 v[104:107], v[174:177], v[202:205], v[104:107]
	v_mfma_f32_16x16x32_bf16 v[96:99], v[184:187], v[202:205], v[96:99]
	v_mfma_f32_16x16x32_bf16 v[88:91], v[174:177], v[210:213], v[88:91]
	v_mfma_f32_16x16x32_bf16 v[80:83], v[184:187], v[210:213], v[80:83]
	v_mfma_f32_16x16x32_bf16 v[72:75], v[174:177], v[218:221], v[72:75]
	v_mfma_f32_16x16x32_bf16 v[64:67], v[184:187], v[218:221], v[64:67]
	s_setprio 0
	s_barrier
	s_add_i32 s24, s47, s27
	v_lshl_add_u64 v[148:149], v[148:149], 0, s[6:7]
	s_mov_b32 m0, s24
	ds_read_b128 v[190:193], v155 offset:49152
	ds_read_b128 v[194:197], v155 offset:50176
	ds_read_b128 v[198:201], v155 offset:51200
	ds_read_b128 v[202:205], v155 offset:52224
	ds_read_b128 v[206:209], v155 offset:53248
	ds_read_b128 v[210:213], v155 offset:54272
	ds_read_b128 v[214:217], v155 offset:55296
	ds_read_b128 v[218:221], v155 offset:56320
	global_load_lds_dwordx4 v[148:149], off
	s_add_i32 m0, s24, 0x2000
	s_add_u32 s22, s22, 0x80080
	v_lshl_add_u64 v[148:149], v[222:223], 0, s[6:7]
	s_addc_u32 s23, s23, 0
	s_add_i32 s24, s48, s27
	global_load_lds_dwordx4 v[148:149], off
	v_lshl_add_u64 v[148:149], s[22:23], 0, v[130:131]
	s_mov_b32 m0, s24
	s_nop 0
	global_load_lds_dwordx4 v[148:149], off
	v_lshl_add_u64 v[148:149], s[22:23], 0, v[134:135]
	s_add_i32 m0, s24, 0x2000
	s_nop 0
	global_load_lds_dwordx4 v[148:149], off
	v_lshl_add_u64 v[148:149], v[224:225], 0, s[6:7]
	s_mov_b32 m0, s34
	s_nop 0
	global_load_lds_dwordx4 v[148:149], off
	v_lshl_add_u64 v[148:149], v[226:227], 0, s[6:7]
	s_mov_b32 m0, s35
	s_nop 0
	global_load_lds_dwordx4 v[148:149], off
	s_waitcnt vmcnt(8)
	s_waitcnt lgkmcnt(0)
	s_barrier
	s_setprio 1
	s_waitcnt lgkmcnt(0)
	v_mfma_f32_16x16x32_bf16 v[60:63], v[144:147], v[190:193], v[60:63]
	v_mfma_f32_16x16x32_bf16 v[52:55], v[162:165], v[190:193], v[52:55]
	v_mfma_f32_16x16x32_bf16 v[44:47], v[144:147], v[198:201], v[44:47]
	v_mfma_f32_16x16x32_bf16 v[36:39], v[162:165], v[198:201], v[36:39]
	v_mfma_f32_16x16x32_bf16 v[28:31], v[144:147], v[206:209], v[28:31]
	v_mfma_f32_16x16x32_bf16 v[20:23], v[162:165], v[206:209], v[20:23]
	v_mfma_f32_16x16x32_bf16 v[12:15], v[144:147], v[214:217], v[12:15]
	v_mfma_f32_16x16x32_bf16 v[4:7], v[162:165], v[214:217], v[4:7]
	v_mfma_f32_16x16x32_bf16 v[60:63], v[158:161], v[194:197], v[60:63]
	v_mfma_f32_16x16x32_bf16 v[52:55], v[166:169], v[194:197], v[52:55]
	v_mfma_f32_16x16x32_bf16 v[44:47], v[158:161], v[202:205], v[44:47]
	v_mfma_f32_16x16x32_bf16 v[36:39], v[166:169], v[202:205], v[36:39]
	v_mfma_f32_16x16x32_bf16 v[28:31], v[158:161], v[210:213], v[28:31]
	v_mfma_f32_16x16x32_bf16 v[20:23], v[166:169], v[210:213], v[20:23]
	v_mfma_f32_16x16x32_bf16 v[12:15], v[158:161], v[218:221], v[12:15]
	v_mfma_f32_16x16x32_bf16 v[4:7], v[166:169], v[218:221], v[4:7]
	s_setprio 0
	s_setprio 1
	v_mfma_f32_16x16x32_bf16 v[56:59], v[170:173], v[190:193], v[56:59]
	v_mfma_f32_16x16x32_bf16 v[48:51], v[178:181], v[190:193], v[48:51]
	v_mfma_f32_16x16x32_bf16 v[40:43], v[170:173], v[198:201], v[40:43]
	v_mfma_f32_16x16x32_bf16 v[32:35], v[178:181], v[198:201], v[32:35]
	v_mfma_f32_16x16x32_bf16 v[24:27], v[170:173], v[206:209], v[24:27]
	v_mfma_f32_16x16x32_bf16 v[16:19], v[178:181], v[206:209], v[16:19]
	v_mfma_f32_16x16x32_bf16 v[8:11], v[170:173], v[214:217], v[8:11]
	v_mfma_f32_16x16x32_bf16 v[0:3], v[178:181], v[214:217], v[0:3]
	v_mfma_f32_16x16x32_bf16 v[56:59], v[174:177], v[194:197], v[56:59]
	v_mfma_f32_16x16x32_bf16 v[48:51], v[184:187], v[194:197], v[48:51]
	v_mfma_f32_16x16x32_bf16 v[40:43], v[174:177], v[202:205], v[40:43]
	v_mfma_f32_16x16x32_bf16 v[32:35], v[184:187], v[202:205], v[32:35]
	v_mfma_f32_16x16x32_bf16 v[24:27], v[174:177], v[210:213], v[24:27]
	v_mfma_f32_16x16x32_bf16 v[16:19], v[184:187], v[210:213], v[16:19]
	v_mfma_f32_16x16x32_bf16 v[8:11], v[174:177], v[218:221], v[8:11]
	v_mfma_f32_16x16x32_bf16 v[0:3], v[184:187], v[218:221], v[0:3]
	s_setprio 0
	s_add_i32 s46, s46, 2
	s_add_u32 s20, s20, 0x100
	s_addc_u32 s21, s21, 0
	s_add_u32 s44, s44, 0x100
	s_addc_u32 s45, s45, 0
	s_cmp_gt_u32 s46, 29
	s_barrier
	s_cbranch_scc0 .LBB0_504
	s_and_b64 vcc, exec, s[8:9]
	s_cbranch_vccz .LBB0_507
	s_barrier

.LBB0_1013:
	ds_read_b128 v[140:143], v149
	ds_read_b128 v[154:157], v149 offset:1024
	ds_read_b128 v[158:161], v149 offset:2048
	ds_read_b128 v[162:165], v149 offset:3072
	ds_read_b128 v[166:169], v150
	ds_read_b128 v[170:173], v150 offset:1024
	ds_read_b128 v[174:177], v150 offset:2048
	ds_read_b128 v[178:181], v150 offset:3072
	s_add_u32 s22, s20, 0x100
	s_addc_u32 s23, s21, 0
	s_cmpk_eq_i32 s48, 0x54
	s_cselect_b32 s27, s1, s23
	s_cselect_b32 s26, s0, s22
	s_cselect_b32 s25, s3, s47
	s_cselect_b32 s24, s2, s46
	v_lshl_add_u64 v[144:145], s[20:21], 0, v[132:133]
	s_add_i32 m0, s29, 0xc000
	ds_read_b128 v[184:187], v151
	ds_read_b128 v[190:193], v151 offset:1024
	ds_read_b128 v[194:197], v151 offset:2048
	ds_read_b128 v[198:201], v151 offset:3072
	ds_read_b128 v[202:205], v151 offset:4096
	ds_read_b128 v[206:209], v151 offset:5120
	ds_read_b128 v[210:213], v151 offset:6144
	ds_read_b128 v[214:217], v151 offset:7168
	global_load_lds_dwordx4 v[144:145], off
	v_lshl_add_u64 v[144:145], s[20:21], 0, v[134:135]
	s_add_i32 m0, s29, 0xe000
	s_nop 0
	global_load_lds_dwordx4 v[144:145], off
	s_waitcnt vmcnt(8)
	s_waitcnt lgkmcnt(0)
	s_barrier
	s_setprio 1
	s_waitcnt lgkmcnt(0)
	v_mfma_f32_16x16x32_bf16 v[124:127], v[140:143], v[184:187], v[124:127]
	v_mfma_f32_16x16x32_bf16 v[120:123], v[158:161], v[184:187], v[120:123]
	v_mfma_f32_16x16x32_bf16 v[108:111], v[140:143], v[194:197], v[108:111]
	v_mfma_f32_16x16x32_bf16 v[104:107], v[158:161], v[194:197], v[104:107]
	v_mfma_f32_16x16x32_bf16 v[92:95], v[140:143], v[202:205], v[92:95]
	v_mfma_f32_16x16x32_bf16 v[88:91], v[158:161], v[202:205], v[88:91]
	v_mfma_f32_16x16x32_bf16 v[76:79], v[140:143], v[210:213], v[76:79]
	v_mfma_f32_16x16x32_bf16 v[72:75], v[158:161], v[210:213], v[72:75]
	v_mfma_f32_16x16x32_bf16 v[124:127], v[154:157], v[190:193], v[124:127]
	v_mfma_f32_16x16x32_bf16 v[120:123], v[162:165], v[190:193], v[120:123]
	v_mfma_f32_16x16x32_bf16 v[108:111], v[154:157], v[198:201], v[108:111]
	v_mfma_f32_16x16x32_bf16 v[104:107], v[162:165], v[198:201], v[104:107]
	v_mfma_f32_16x16x32_bf16 v[92:95], v[154:157], v[206:209], v[92:95]
	v_mfma_f32_16x16x32_bf16 v[88:91], v[162:165], v[206:209], v[88:91]
	v_mfma_f32_16x16x32_bf16 v[76:79], v[154:157], v[214:217], v[76:79]
	v_mfma_f32_16x16x32_bf16 v[72:75], v[162:165], v[214:217], v[72:75]
	s_setprio 0
	s_setprio 1
	v_mfma_f32_16x16x32_bf16 v[116:119], v[166:169], v[184:187], v[116:119]
	v_mfma_f32_16x16x32_bf16 v[112:115], v[174:177], v[184:187], v[112:115]
	v_mfma_f32_16x16x32_bf16 v[100:103], v[166:169], v[194:197], v[100:103]
	v_mfma_f32_16x16x32_bf16 v[96:99], v[174:177], v[194:197], v[96:99]
	v_mfma_f32_16x16x32_bf16 v[84:87], v[166:169], v[202:205], v[84:87]
	v_mfma_f32_16x16x32_bf16 v[80:83], v[174:177], v[202:205], v[80:83]
	v_mfma_f32_16x16x32_bf16 v[68:71], v[166:169], v[210:213], v[68:71]
	v_mfma_f32_16x16x32_bf16 v[64:67], v[174:177], v[210:213], v[64:67]
	v_mfma_f32_16x16x32_bf16 v[116:119], v[170:173], v[190:193], v[116:119]
	v_mfma_f32_16x16x32_bf16 v[112:115], v[178:181], v[190:193], v[112:115]
	v_mfma_f32_16x16x32_bf16 v[100:103], v[170:173], v[198:201], v[100:103]
	v_mfma_f32_16x16x32_bf16 v[96:99], v[178:181], v[198:201], v[96:99]
	v_mfma_f32_16x16x32_bf16 v[84:87], v[170:173], v[206:209], v[84:87]
	v_mfma_f32_16x16x32_bf16 v[80:83], v[178:181], v[206:209], v[80:83]
	v_mfma_f32_16x16x32_bf16 v[68:71], v[170:173], v[214:217], v[68:71]
	v_mfma_f32_16x16x32_bf16 v[64:67], v[178:181], v[214:217], v[64:67]
	s_setprio 0
	s_barrier
	s_add_i32 s20, s40, s28
	v_lshl_add_u64 v[144:145], s[24:25], 0, v[128:129]
	s_mov_b32 m0, s20
	ds_read_b128 v[184:187], v151 offset:16384
	ds_read_b128 v[190:193], v151 offset:17408
	ds_read_b128 v[194:197], v151 offset:18432
	ds_read_b128 v[198:201], v151 offset:19456
	ds_read_b128 v[202:205], v151 offset:20480
	ds_read_b128 v[206:209], v151 offset:21504
	ds_read_b128 v[210:213], v151 offset:22528
	ds_read_b128 v[214:217], v151 offset:23552
	global_load_lds_dwordx4 v[144:145], off
	s_add_i32 m0, s20, 0x2000
	s_add_u32 s20, s24, 0x160000
	v_lshl_add_u64 v[218:219], s[24:25], 0, v[130:131]
	s_addc_u32 s21, s25, 0
	s_add_i32 s49, s41, s28
	global_load_lds_dwordx4 v[218:219], off
	v_lshl_add_u64 v[220:221], s[20:21], 0, v[128:129]
	s_mov_b32 m0, s49
	v_lshl_add_u64 v[222:223], s[26:27], 0, v[130:131]
	global_load_lds_dwordx4 v[220:221], off
	v_lshl_add_u64 v[220:221], s[20:21], 0, v[130:131]
	s_add_i32 m0, s49, 0x2000
	s_nop 0
	global_load_lds_dwordx4 v[220:221], off
	v_lshl_add_u64 v[220:221], s[26:27], 0, v[128:129]
	s_mov_b32 m0, s29
	s_nop 0
	global_load_lds_dwordx4 v[220:221], off
	s_mov_b32 m0, s30
	s_nop 0
	global_load_lds_dwordx4 v[222:223], off
	s_waitcnt vmcnt(8)
	s_waitcnt lgkmcnt(0)
	s_barrier
	s_setprio 1
	s_waitcnt lgkmcnt(0)
	v_mfma_f32_16x16x32_bf16 v[60:63], v[140:143], v[184:187], v[60:63]
	v_mfma_f32_16x16x32_bf16 v[56:59], v[158:161], v[184:187], v[56:59]
	v_mfma_f32_16x16x32_bf16 v[44:47], v[140:143], v[194:197], v[44:47]
	v_mfma_f32_16x16x32_bf16 v[40:43], v[158:161], v[194:197], v[40:43]
	v_mfma_f32_16x16x32_bf16 v[28:31], v[140:143], v[202:205], v[28:31]
	v_mfma_f32_16x16x32_bf16 v[24:27], v[158:161], v[202:205], v[24:27]
	v_mfma_f32_16x16x32_bf16 v[12:15], v[140:143], v[210:213], v[12:15]
	v_mfma_f32_16x16x32_bf16 v[8:11], v[158:161], v[210:213], v[8:11]
	v_mfma_f32_16x16x32_bf16 v[60:63], v[154:157], v[190:193], v[60:63]
	v_mfma_f32_16x16x32_bf16 v[56:59], v[162:165], v[190:193], v[56:59]
	v_mfma_f32_16x16x32_bf16 v[44:47], v[154:157], v[198:201], v[44:47]
	v_mfma_f32_16x16x32_bf16 v[40:43], v[162:165], v[198:201], v[40:43]
	v_mfma_f32_16x16x32_bf16 v[28:31], v[154:157], v[206:209], v[28:31]
	v_mfma_f32_16x16x32_bf16 v[24:27], v[162:165], v[206:209], v[24:27]
	v_mfma_f32_16x16x32_bf16 v[12:15], v[154:157], v[214:217], v[12:15]
	v_mfma_f32_16x16x32_bf16 v[8:11], v[162:165], v[214:217], v[8:11]
	s_setprio 0
	s_setprio 1
	v_mfma_f32_16x16x32_bf16 v[52:55], v[166:169], v[184:187], v[52:55]
	v_mfma_f32_16x16x32_bf16 v[48:51], v[174:177], v[184:187], v[48:51]
	v_mfma_f32_16x16x32_bf16 v[36:39], v[166:169], v[194:197], v[36:39]
	v_mfma_f32_16x16x32_bf16 v[32:35], v[174:177], v[194:197], v[32:35]
	v_mfma_f32_16x16x32_bf16 v[20:23], v[166:169], v[202:205], v[20:23]
	v_mfma_f32_16x16x32_bf16 v[16:19], v[174:177], v[202:205], v[16:19]
	v_mfma_f32_16x16x32_bf16 v[4:7], v[166:169], v[210:213], v[4:7]
	v_mfma_f32_16x16x32_bf16 v[0:3], v[174:177], v[210:213], v[0:3]
	v_mfma_f32_16x16x32_bf16 v[52:55], v[170:173], v[190:193], v[52:55]
	v_mfma_f32_16x16x32_bf16 v[48:51], v[178:181], v[190:193], v[48:51]
	v_mfma_f32_16x16x32_bf16 v[36:39], v[170:173], v[198:201], v[36:39]
	v_mfma_f32_16x16x32_bf16 v[32:35], v[178:181], v[198:201], v[32:35]
	v_mfma_f32_16x16x32_bf16 v[20:23], v[170:173], v[206:209], v[20:23]
	v_mfma_f32_16x16x32_bf16 v[16:19], v[178:181], v[206:209], v[16:19]
	v_mfma_f32_16x16x32_bf16 v[4:7], v[170:173], v[214:217], v[4:7]
	v_mfma_f32_16x16x32_bf16 v[0:3], v[178:181], v[214:217], v[0:3]
	s_setprio 0
	s_barrier
	s_add_i32 s49, 0, 0x18000
	v_add_u32_e32 v153, s49, v147
	s_add_i32 s50, 0, 0x1c000
	ds_read_b128 v[140:143], v153
	ds_read_b128 v[154:157], v153 offset:1024
	ds_read_b128 v[158:161], v153 offset:2048
	ds_read_b128 v[162:165], v153 offset:3072
	v_add_u32_e32 v153, s50, v147
	ds_read_b128 v[166:169], v153
	ds_read_b128 v[170:173], v153 offset:1024
	ds_read_b128 v[174:177], v153 offset:2048
	ds_read_b128 v[178:181], v153 offset:3072
	s_add_u32 s20, s26, 0x160000
	s_addc_u32 s21, s27, 0
	s_mov_b32 m0, s31
	v_lshl_add_u64 v[224:225], s[20:21], 0, v[128:129]
	ds_read_b128 v[184:187], v151 offset:32768
	ds_read_b128 v[190:193], v151 offset:33792
	ds_read_b128 v[194:197], v151 offset:34816
	ds_read_b128 v[198:201], v151 offset:35840
	ds_read_b128 v[202:205], v151 offset:36864
	ds_read_b128 v[206:209], v151 offset:37888
	ds_read_b128 v[210:213], v151 offset:38912
	ds_read_b128 v[214:217], v151 offset:39936
	global_load_lds_dwordx4 v[224:225], off
	v_lshl_add_u64 v[224:225], s[20:21], 0, v[130:131]
	s_mov_b32 m0, s33
	s_nop 0
	global_load_lds_dwordx4 v[224:225], off
	s_waitcnt vmcnt(8)
	s_waitcnt lgkmcnt(0)
	s_barrier
	s_setprio 1
	s_waitcnt lgkmcnt(0)
	v_mfma_f32_16x16x32_bf16 v[124:127], v[140:143], v[184:187], v[124:127]
	v_mfma_f32_16x16x32_bf16 v[120:123], v[158:161], v[184:187], v[120:123]
	v_mfma_f32_16x16x32_bf16 v[108:111], v[140:143], v[194:197], v[108:111]
	v_mfma_f32_16x16x32_bf16 v[104:107], v[158:161], v[194:197], v[104:107]
	v_mfma_f32_16x16x32_bf16 v[92:95], v[140:143], v[202:205], v[92:95]
	v_mfma_f32_16x16x32_bf16 v[88:91], v[158:161], v[202:205], v[88:91]
	v_mfma_f32_16x16x32_bf16 v[76:79], v[140:143], v[210:213], v[76:79]
	v_mfma_f32_16x16x32_bf16 v[72:75], v[158:161], v[210:213], v[72:75]
	v_mfma_f32_16x16x32_bf16 v[124:127], v[154:157], v[190:193], v[124:127]
	v_mfma_f32_16x16x32_bf16 v[120:123], v[162:165], v[190:193], v[120:123]
	v_mfma_f32_16x16x32_bf16 v[108:111], v[154:157], v[198:201], v[108:111]
	v_mfma_f32_16x16x32_bf16 v[104:107], v[162:165], v[198:201], v[104:107]
	v_mfma_f32_16x16x32_bf16 v[92:95], v[154:157], v[206:209], v[92:95]
	v_mfma_f32_16x16x32_bf16 v[88:91], v[162:165], v[206:209], v[88:91]
	v_mfma_f32_16x16x32_bf16 v[76:79], v[154:157], v[214:217], v[76:79]
	v_mfma_f32_16x16x32_bf16 v[72:75], v[162:165], v[214:217], v[72:75]
	s_setprio 0
	s_setprio 1
	v_mfma_f32_16x16x32_bf16 v[116:119], v[166:169], v[184:187], v[116:119]
	v_mfma_f32_16x16x32_bf16 v[112:115], v[174:177], v[184:187], v[112:115]
	v_mfma_f32_16x16x32_bf16 v[100:103], v[166:169], v[194:197], v[100:103]
	v_mfma_f32_16x16x32_bf16 v[96:99], v[174:177], v[194:197], v[96:99]
	v_mfma_f32_16x16x32_bf16 v[84:87], v[166:169], v[202:205], v[84:87]
	v_mfma_f32_16x16x32_bf16 v[80:83], v[174:177], v[202:205], v[80:83]
	v_mfma_f32_16x16x32_bf16 v[68:71], v[166:169], v[210:213], v[68:71]
	v_mfma_f32_16x16x32_bf16 v[64:67], v[174:177], v[210:213], v[64:67]
	v_mfma_f32_16x16x32_bf16 v[116:119], v[170:173], v[190:193], v[116:119]
	v_mfma_f32_16x16x32_bf16 v[112:115], v[178:181], v[190:193], v[112:115]
	v_mfma_f32_16x16x32_bf16 v[100:103], v[170:173], v[198:201], v[100:103]
	v_mfma_f32_16x16x32_bf16 v[96:99], v[178:181], v[198:201], v[96:99]
	v_mfma_f32_16x16x32_bf16 v[84:87], v[170:173], v[206:209], v[84:87]
	v_mfma_f32_16x16x32_bf16 v[80:83], v[178:181], v[206:209], v[80:83]
	v_mfma_f32_16x16x32_bf16 v[68:71], v[170:173], v[214:217], v[68:71]
	v_mfma_f32_16x16x32_bf16 v[64:67], v[178:181], v[214:217], v[64:67]
	s_setprio 0
	s_barrier
	s_add_i32 s20, s49, s28
	v_lshl_add_u64 v[144:145], v[144:145], 0, s[12:13]
	s_mov_b32 m0, s20
	ds_read_b128 v[184:187], v151 offset:49152
	ds_read_b128 v[190:193], v151 offset:50176
	ds_read_b128 v[194:197], v151 offset:51200
	ds_read_b128 v[198:201], v151 offset:52224
	ds_read_b128 v[202:205], v151 offset:53248
	ds_read_b128 v[206:209], v151 offset:54272
	ds_read_b128 v[210:213], v151 offset:55296
	ds_read_b128 v[214:217], v151 offset:56320
	global_load_lds_dwordx4 v[144:145], off
	s_add_i32 m0, s20, 0x2000
	s_add_u32 s20, s24, 0x160080
	v_lshl_add_u64 v[144:145], v[218:219], 0, s[12:13]
	s_addc_u32 s21, s25, 0
	s_add_i32 s24, s50, s28
	global_load_lds_dwordx4 v[144:145], off
	v_lshl_add_u64 v[144:145], s[20:21], 0, v[128:129]
	s_mov_b32 m0, s24
	s_nop 0
	global_load_lds_dwordx4 v[144:145], off
	v_lshl_add_u64 v[144:145], s[20:21], 0, v[130:131]
	s_add_i32 m0, s24, 0x2000
	s_nop 0
	global_load_lds_dwordx4 v[144:145], off
	v_lshl_add_u64 v[144:145], v[220:221], 0, s[12:13]
	s_mov_b32 m0, s35
	s_nop 0
	global_load_lds_dwordx4 v[144:145], off
	v_lshl_add_u64 v[144:145], v[222:223], 0, s[12:13]
	s_mov_b32 m0, s36
	s_nop 0
	global_load_lds_dwordx4 v[144:145], off
	s_waitcnt vmcnt(8)
	s_waitcnt lgkmcnt(0)
	s_barrier
	s_setprio 1
	s_waitcnt lgkmcnt(0)
	v_mfma_f32_16x16x32_bf16 v[60:63], v[140:143], v[184:187], v[60:63]
	v_mfma_f32_16x16x32_bf16 v[56:59], v[158:161], v[184:187], v[56:59]
	v_mfma_f32_16x16x32_bf16 v[44:47], v[140:143], v[194:197], v[44:47]
	v_mfma_f32_16x16x32_bf16 v[40:43], v[158:161], v[194:197], v[40:43]
	v_mfma_f32_16x16x32_bf16 v[28:31], v[140:143], v[202:205], v[28:31]
	v_mfma_f32_16x16x32_bf16 v[24:27], v[158:161], v[202:205], v[24:27]
	v_mfma_f32_16x16x32_bf16 v[12:15], v[140:143], v[210:213], v[12:15]
	v_mfma_f32_16x16x32_bf16 v[8:11], v[158:161], v[210:213], v[8:11]
	v_mfma_f32_16x16x32_bf16 v[60:63], v[154:157], v[190:193], v[60:63]
	v_mfma_f32_16x16x32_bf16 v[56:59], v[162:165], v[190:193], v[56:59]
	v_mfma_f32_16x16x32_bf16 v[44:47], v[154:157], v[198:201], v[44:47]
	v_mfma_f32_16x16x32_bf16 v[40:43], v[162:165], v[198:201], v[40:43]
	v_mfma_f32_16x16x32_bf16 v[28:31], v[154:157], v[206:209], v[28:31]
	v_mfma_f32_16x16x32_bf16 v[24:27], v[162:165], v[206:209], v[24:27]
	v_mfma_f32_16x16x32_bf16 v[12:15], v[154:157], v[214:217], v[12:15]
	v_mfma_f32_16x16x32_bf16 v[8:11], v[162:165], v[214:217], v[8:11]
	s_setprio 0
	s_setprio 1
	v_mfma_f32_16x16x32_bf16 v[52:55], v[166:169], v[184:187], v[52:55]
	v_mfma_f32_16x16x32_bf16 v[48:51], v[174:177], v[184:187], v[48:51]
	v_mfma_f32_16x16x32_bf16 v[36:39], v[166:169], v[194:197], v[36:39]
	v_mfma_f32_16x16x32_bf16 v[32:35], v[174:177], v[194:197], v[32:35]
	v_mfma_f32_16x16x32_bf16 v[20:23], v[166:169], v[202:205], v[20:23]
	v_mfma_f32_16x16x32_bf16 v[16:19], v[174:177], v[202:205], v[16:19]
	v_mfma_f32_16x16x32_bf16 v[4:7], v[166:169], v[210:213], v[4:7]
	v_mfma_f32_16x16x32_bf16 v[0:3], v[174:177], v[210:213], v[0:3]
	v_mfma_f32_16x16x32_bf16 v[52:55], v[170:173], v[190:193], v[52:55]
	v_mfma_f32_16x16x32_bf16 v[48:51], v[178:181], v[190:193], v[48:51]
	v_mfma_f32_16x16x32_bf16 v[36:39], v[170:173], v[198:201], v[36:39]
	v_mfma_f32_16x16x32_bf16 v[32:35], v[178:181], v[198:201], v[32:35]
	v_mfma_f32_16x16x32_bf16 v[20:23], v[170:173], v[206:209], v[20:23]
	v_mfma_f32_16x16x32_bf16 v[16:19], v[178:181], v[206:209], v[16:19]
	v_mfma_f32_16x16x32_bf16 v[4:7], v[170:173], v[214:217], v[4:7]
	v_mfma_f32_16x16x32_bf16 v[0:3], v[178:181], v[214:217], v[0:3]
	s_setprio 0
	s_add_i32 s48, s48, 2
	s_add_u32 s46, s46, 0x100
	s_addc_u32 s47, s47, 0
	s_cmpk_gt_u32 s48, 0x55
	s_mov_b64 s[20:21], s[22:23]
	s_barrier
	s_cbranch_scc0 .LBB0_1013
	s_and_b64 vcc, exec, s[18:19]
	s_cbranch_vccz .LBB0_1016
	s_barrier

.LBB0_1114:
	ds_read_b128 v[146:149], v156
	ds_read_b128 v[160:163], v156 offset:1024
	ds_read_b128 v[164:167], v156 offset:2048
	ds_read_b128 v[168:171], v156 offset:3072
	ds_read_b128 v[172:175], v157
	ds_read_b128 v[176:179], v157 offset:1024
	ds_read_b128 v[184:187], v157 offset:2048
	ds_read_b128 v[190:193], v157 offset:3072
	s_add_u32 s36, s8, 0xfff80080
	s_addc_u32 s37, s9, -1
	s_cmp_eq_u32 s58, 28
	s_cselect_b32 s39, s1, s37
	s_cselect_b32 s38, s7, s36
	s_cselect_b32 s37, s27, s57
	s_cselect_b32 s36, s29, s56
	v_lshl_add_u64 v[150:151], s[8:9], 0, v[138:139]
	s_add_i32 m0, s40, 0xc000
	ds_read_b128 v[194:197], v158
	ds_read_b128 v[198:201], v158 offset:1024
	ds_read_b128 v[202:205], v158 offset:2048
	ds_read_b128 v[206:209], v158 offset:3072
	ds_read_b128 v[210:213], v158 offset:4096
	ds_read_b128 v[214:217], v158 offset:5120
	ds_read_b128 v[218:221], v158 offset:6144
	ds_read_b128 v[222:225], v158 offset:7168
	global_load_lds_dwordx4 v[150:151], off
	v_lshl_add_u64 v[150:151], s[8:9], 0, v[140:141]
	s_add_i32 m0, s40, 0xe000
	s_nop 0
	global_load_lds_dwordx4 v[150:151], off
	s_waitcnt vmcnt(8)
	s_waitcnt lgkmcnt(0)
	s_barrier
	s_setprio 1
	s_waitcnt lgkmcnt(0)
	v_mfma_f32_16x16x32_bf16 v[124:127], v[146:149], v[194:197], v[124:127]
	v_mfma_f32_16x16x32_bf16 v[120:123], v[164:167], v[194:197], v[120:123]
	v_mfma_f32_16x16x32_bf16 v[108:111], v[146:149], v[202:205], v[108:111]
	v_mfma_f32_16x16x32_bf16 v[104:107], v[164:167], v[202:205], v[104:107]
	v_mfma_f32_16x16x32_bf16 v[92:95], v[146:149], v[210:213], v[92:95]
	v_mfma_f32_16x16x32_bf16 v[88:91], v[164:167], v[210:213], v[88:91]
	v_mfma_f32_16x16x32_bf16 v[76:79], v[146:149], v[218:221], v[76:79]
	v_mfma_f32_16x16x32_bf16 v[72:75], v[164:167], v[218:221], v[72:75]
	v_mfma_f32_16x16x32_bf16 v[124:127], v[160:163], v[198:201], v[124:127]
	v_mfma_f32_16x16x32_bf16 v[120:123], v[168:171], v[198:201], v[120:123]
	v_mfma_f32_16x16x32_bf16 v[108:111], v[160:163], v[206:209], v[108:111]
	v_mfma_f32_16x16x32_bf16 v[104:107], v[168:171], v[206:209], v[104:107]
	v_mfma_f32_16x16x32_bf16 v[92:95], v[160:163], v[214:217], v[92:95]
	v_mfma_f32_16x16x32_bf16 v[88:91], v[168:171], v[214:217], v[88:91]
	v_mfma_f32_16x16x32_bf16 v[76:79], v[160:163], v[222:225], v[76:79]
	v_mfma_f32_16x16x32_bf16 v[72:75], v[168:171], v[222:225], v[72:75]
	s_setprio 0
	s_setprio 1
	v_mfma_f32_16x16x32_bf16 v[116:119], v[172:175], v[194:197], v[116:119]
	v_mfma_f32_16x16x32_bf16 v[112:115], v[184:187], v[194:197], v[112:115]
	v_mfma_f32_16x16x32_bf16 v[100:103], v[172:175], v[202:205], v[100:103]
	v_mfma_f32_16x16x32_bf16 v[96:99], v[184:187], v[202:205], v[96:99]
	v_mfma_f32_16x16x32_bf16 v[84:87], v[172:175], v[210:213], v[84:87]
	v_mfma_f32_16x16x32_bf16 v[80:83], v[184:187], v[210:213], v[80:83]
	v_mfma_f32_16x16x32_bf16 v[68:71], v[172:175], v[218:221], v[68:71]
	v_mfma_f32_16x16x32_bf16 v[64:67], v[184:187], v[218:221], v[64:67]
	v_mfma_f32_16x16x32_bf16 v[116:119], v[176:179], v[198:201], v[116:119]
	v_mfma_f32_16x16x32_bf16 v[112:115], v[190:193], v[198:201], v[112:115]
	v_mfma_f32_16x16x32_bf16 v[100:103], v[176:179], v[206:209], v[100:103]
	v_mfma_f32_16x16x32_bf16 v[96:99], v[190:193], v[206:209], v[96:99]
	v_mfma_f32_16x16x32_bf16 v[84:87], v[176:179], v[214:217], v[84:87]
	v_mfma_f32_16x16x32_bf16 v[80:83], v[190:193], v[214:217], v[80:83]
	v_mfma_f32_16x16x32_bf16 v[68:71], v[176:179], v[222:225], v[68:71]
	v_mfma_f32_16x16x32_bf16 v[64:67], v[190:193], v[222:225], v[64:67]
	s_setprio 0
	s_barrier
	s_add_i32 s59, s50, s33
	v_lshl_add_u64 v[150:151], s[36:37], 0, v[130:131]
	s_mov_b32 m0, s59
	ds_read_b128 v[194:197], v158 offset:16384
	ds_read_b128 v[198:201], v158 offset:17408
	ds_read_b128 v[202:205], v158 offset:18432
	ds_read_b128 v[206:209], v158 offset:19456
	ds_read_b128 v[210:213], v158 offset:20480
	ds_read_b128 v[214:217], v158 offset:21504
	ds_read_b128 v[218:221], v158 offset:22528
	ds_read_b128 v[222:225], v158 offset:23552
	global_load_lds_dwordx4 v[150:151], off
	s_add_i32 m0, s59, 0x2000
	s_add_u32 s60, s36, 0x80000
	v_lshl_add_u64 v[180:181], s[36:37], 0, v[134:135]
	s_addc_u32 s61, s37, 0
	s_add_i32 s59, s51, s33
	global_load_lds_dwordx4 v[180:181], off
	v_lshl_add_u64 v[226:227], s[60:61], 0, v[130:131]
	s_mov_b32 m0, s59
	v_lshl_add_u64 v[228:229], s[38:39], 0, v[132:133]
	global_load_lds_dwordx4 v[226:227], off
	v_lshl_add_u64 v[226:227], s[60:61], 0, v[134:135]
	s_add_i32 m0, s59, 0x2000
	s_nop 0
	global_load_lds_dwordx4 v[226:227], off
	v_lshl_add_u64 v[226:227], s[38:39], 0, v[128:129]
	s_mov_b32 m0, s40
	s_nop 0
	global_load_lds_dwordx4 v[226:227], off
	s_mov_b32 m0, s41
	s_nop 0
	global_load_lds_dwordx4 v[228:229], off
	s_waitcnt vmcnt(8)
	s_waitcnt lgkmcnt(0)
	s_barrier
	s_setprio 1
	s_waitcnt lgkmcnt(0)
	v_mfma_f32_16x16x32_bf16 v[60:63], v[146:149], v[194:197], v[60:63]
	v_mfma_f32_16x16x32_bf16 v[56:59], v[164:167], v[194:197], v[56:59]
	v_mfma_f32_16x16x32_bf16 v[44:47], v[146:149], v[202:205], v[44:47]
	v_mfma_f32_16x16x32_bf16 v[40:43], v[164:167], v[202:205], v[40:43]
	v_mfma_f32_16x16x32_bf16 v[28:31], v[146:149], v[210:213], v[28:31]
	v_mfma_f32_16x16x32_bf16 v[24:27], v[164:167], v[210:213], v[24:27]
	v_mfma_f32_16x16x32_bf16 v[12:15], v[146:149], v[218:221], v[12:15]
	v_mfma_f32_16x16x32_bf16 v[8:11], v[164:167], v[218:221], v[8:11]
	v_mfma_f32_16x16x32_bf16 v[60:63], v[160:163], v[198:201], v[60:63]
	v_mfma_f32_16x16x32_bf16 v[56:59], v[168:171], v[198:201], v[56:59]
	v_mfma_f32_16x16x32_bf16 v[44:47], v[160:163], v[206:209], v[44:47]
	v_mfma_f32_16x16x32_bf16 v[40:43], v[168:171], v[206:209], v[40:43]
	v_mfma_f32_16x16x32_bf16 v[28:31], v[160:163], v[214:217], v[28:31]
	v_mfma_f32_16x16x32_bf16 v[24:27], v[168:171], v[214:217], v[24:27]
	v_mfma_f32_16x16x32_bf16 v[12:15], v[160:163], v[222:225], v[12:15]
	v_mfma_f32_16x16x32_bf16 v[8:11], v[168:171], v[222:225], v[8:11]
	s_setprio 0
	s_setprio 1
	v_mfma_f32_16x16x32_bf16 v[52:55], v[172:175], v[194:197], v[52:55]
	v_mfma_f32_16x16x32_bf16 v[48:51], v[184:187], v[194:197], v[48:51]
	v_mfma_f32_16x16x32_bf16 v[36:39], v[172:175], v[202:205], v[36:39]
	v_mfma_f32_16x16x32_bf16 v[32:35], v[184:187], v[202:205], v[32:35]
	v_mfma_f32_16x16x32_bf16 v[20:23], v[172:175], v[210:213], v[20:23]
	v_mfma_f32_16x16x32_bf16 v[16:19], v[184:187], v[210:213], v[16:19]
	v_mfma_f32_16x16x32_bf16 v[4:7], v[172:175], v[218:221], v[4:7]
	v_mfma_f32_16x16x32_bf16 v[0:3], v[184:187], v[218:221], v[0:3]
	v_mfma_f32_16x16x32_bf16 v[52:55], v[176:179], v[198:201], v[52:55]
	v_mfma_f32_16x16x32_bf16 v[48:51], v[190:193], v[198:201], v[48:51]
	v_mfma_f32_16x16x32_bf16 v[36:39], v[176:179], v[206:209], v[36:39]
	v_mfma_f32_16x16x32_bf16 v[32:35], v[190:193], v[206:209], v[32:35]
	v_mfma_f32_16x16x32_bf16 v[20:23], v[176:179], v[214:217], v[20:23]
	v_mfma_f32_16x16x32_bf16 v[16:19], v[190:193], v[214:217], v[16:19]
	v_mfma_f32_16x16x32_bf16 v[4:7], v[176:179], v[222:225], v[4:7]
	v_mfma_f32_16x16x32_bf16 v[0:3], v[190:193], v[222:225], v[0:3]
	s_setprio 0
	s_barrier
	s_add_i32 s59, 0, 0x18000
	v_add_u32_e32 v152, s59, v154
	s_add_i32 s60, 0, 0x1c000
	ds_read_b128 v[146:149], v152
	ds_read_b128 v[160:163], v152 offset:1024
	ds_read_b128 v[164:167], v152 offset:2048
	ds_read_b128 v[168:171], v152 offset:3072
	v_add_u32_e32 v152, s60, v154
	ds_read_b128 v[172:175], v152
	ds_read_b128 v[176:179], v152 offset:1024
	ds_read_b128 v[184:187], v152 offset:2048
	ds_read_b128 v[190:193], v152 offset:3072
	s_add_u32 s38, s38, 0x80000
	s_addc_u32 s39, s39, 0
	s_mov_b32 m0, s42
	v_lshl_add_u64 v[230:231], s[38:39], 0, v[128:129]
	ds_read_b128 v[194:197], v158 offset:32768
	ds_read_b128 v[198:201], v158 offset:33792
	ds_read_b128 v[202:205], v158 offset:34816
	ds_read_b128 v[206:209], v158 offset:35840
	ds_read_b128 v[210:213], v158 offset:36864
	ds_read_b128 v[214:217], v158 offset:37888
	ds_read_b128 v[218:221], v158 offset:38912
	ds_read_b128 v[222:225], v158 offset:39936
	global_load_lds_dwordx4 v[230:231], off
	v_lshl_add_u64 v[230:231], s[38:39], 0, v[132:133]
	s_mov_b32 m0, s43
	s_nop 0
	global_load_lds_dwordx4 v[230:231], off
	s_waitcnt vmcnt(8)
	s_waitcnt lgkmcnt(0)
	s_barrier
	s_setprio 1
	s_waitcnt lgkmcnt(0)
	v_mfma_f32_16x16x32_bf16 v[124:127], v[146:149], v[194:197], v[124:127]
	v_mfma_f32_16x16x32_bf16 v[120:123], v[164:167], v[194:197], v[120:123]
	v_mfma_f32_16x16x32_bf16 v[108:111], v[146:149], v[202:205], v[108:111]
	v_mfma_f32_16x16x32_bf16 v[104:107], v[164:167], v[202:205], v[104:107]
	v_mfma_f32_16x16x32_bf16 v[92:95], v[146:149], v[210:213], v[92:95]
	v_mfma_f32_16x16x32_bf16 v[88:91], v[164:167], v[210:213], v[88:91]
	v_mfma_f32_16x16x32_bf16 v[76:79], v[146:149], v[218:221], v[76:79]
	v_mfma_f32_16x16x32_bf16 v[72:75], v[164:167], v[218:221], v[72:75]
	v_mfma_f32_16x16x32_bf16 v[124:127], v[160:163], v[198:201], v[124:127]
	v_mfma_f32_16x16x32_bf16 v[120:123], v[168:171], v[198:201], v[120:123]
	v_mfma_f32_16x16x32_bf16 v[108:111], v[160:163], v[206:209], v[108:111]
	v_mfma_f32_16x16x32_bf16 v[104:107], v[168:171], v[206:209], v[104:107]
	v_mfma_f32_16x16x32_bf16 v[92:95], v[160:163], v[214:217], v[92:95]
	v_mfma_f32_16x16x32_bf16 v[88:91], v[168:171], v[214:217], v[88:91]
	v_mfma_f32_16x16x32_bf16 v[76:79], v[160:163], v[222:225], v[76:79]
	v_mfma_f32_16x16x32_bf16 v[72:75], v[168:171], v[222:225], v[72:75]
	s_setprio 0
	s_setprio 1
	v_mfma_f32_16x16x32_bf16 v[116:119], v[172:175], v[194:197], v[116:119]
	v_mfma_f32_16x16x32_bf16 v[112:115], v[184:187], v[194:197], v[112:115]
	v_mfma_f32_16x16x32_bf16 v[100:103], v[172:175], v[202:205], v[100:103]
	v_mfma_f32_16x16x32_bf16 v[96:99], v[184:187], v[202:205], v[96:99]
	v_mfma_f32_16x16x32_bf16 v[84:87], v[172:175], v[210:213], v[84:87]
	v_mfma_f32_16x16x32_bf16 v[80:83], v[184:187], v[210:213], v[80:83]
	v_mfma_f32_16x16x32_bf16 v[68:71], v[172:175], v[218:221], v[68:71]
	v_mfma_f32_16x16x32_bf16 v[64:67], v[184:187], v[218:221], v[64:67]
	v_mfma_f32_16x16x32_bf16 v[116:119], v[176:179], v[198:201], v[116:119]
	v_mfma_f32_16x16x32_bf16 v[112:115], v[190:193], v[198:201], v[112:115]
	v_mfma_f32_16x16x32_bf16 v[100:103], v[176:179], v[206:209], v[100:103]
	v_mfma_f32_16x16x32_bf16 v[96:99], v[190:193], v[206:209], v[96:99]
	v_mfma_f32_16x16x32_bf16 v[84:87], v[176:179], v[214:217], v[84:87]
	v_mfma_f32_16x16x32_bf16 v[80:83], v[190:193], v[214:217], v[80:83]
	v_mfma_f32_16x16x32_bf16 v[68:71], v[176:179], v[222:225], v[68:71]
	v_mfma_f32_16x16x32_bf16 v[64:67], v[190:193], v[222:225], v[64:67]
	s_setprio 0
	s_barrier
	s_add_i32 s38, s59, s33
	v_lshl_add_u64 v[150:151], v[150:151], 0, s[20:21]
	s_mov_b32 m0, s38
	ds_read_b128 v[194:197], v158 offset:49152
	ds_read_b128 v[198:201], v158 offset:50176
	ds_read_b128 v[202:205], v158 offset:51200
	ds_read_b128 v[206:209], v158 offset:52224
	ds_read_b128 v[210:213], v158 offset:53248
	ds_read_b128 v[214:217], v158 offset:54272
	ds_read_b128 v[218:221], v158 offset:55296
	ds_read_b128 v[222:225], v158 offset:56320
	global_load_lds_dwordx4 v[150:151], off
	s_add_i32 m0, s38, 0x2000
	s_add_u32 s36, s36, 0x80080
	v_lshl_add_u64 v[150:151], v[180:181], 0, s[20:21]
	s_addc_u32 s37, s37, 0
	s_add_i32 s38, s60, s33
	global_load_lds_dwordx4 v[150:151], off
	v_lshl_add_u64 v[150:151], s[36:37], 0, v[130:131]
	s_mov_b32 m0, s38
	s_nop 0
	global_load_lds_dwordx4 v[150:151], off
	v_lshl_add_u64 v[150:151], s[36:37], 0, v[134:135]
	s_add_i32 m0, s38, 0x2000
	s_nop 0
	global_load_lds_dwordx4 v[150:151], off
	v_lshl_add_u64 v[150:151], v[226:227], 0, s[20:21]
	s_mov_b32 m0, s45
	s_nop 0
	global_load_lds_dwordx4 v[150:151], off
	v_lshl_add_u64 v[150:151], v[228:229], 0, s[20:21]
	s_mov_b32 m0, s46
	s_nop 0
	global_load_lds_dwordx4 v[150:151], off
	s_waitcnt vmcnt(8)
	s_waitcnt lgkmcnt(0)
	s_barrier
	s_setprio 1
	s_waitcnt lgkmcnt(0)
	v_mfma_f32_16x16x32_bf16 v[60:63], v[146:149], v[194:197], v[60:63]
	v_mfma_f32_16x16x32_bf16 v[56:59], v[164:167], v[194:197], v[56:59]
	v_mfma_f32_16x16x32_bf16 v[44:47], v[146:149], v[202:205], v[44:47]
	v_mfma_f32_16x16x32_bf16 v[40:43], v[164:167], v[202:205], v[40:43]
	v_mfma_f32_16x16x32_bf16 v[28:31], v[146:149], v[210:213], v[28:31]
	v_mfma_f32_16x16x32_bf16 v[24:27], v[164:167], v[210:213], v[24:27]
	v_mfma_f32_16x16x32_bf16 v[12:15], v[146:149], v[218:221], v[12:15]
	v_mfma_f32_16x16x32_bf16 v[8:11], v[164:167], v[218:221], v[8:11]
	v_mfma_f32_16x16x32_bf16 v[60:63], v[160:163], v[198:201], v[60:63]
	v_mfma_f32_16x16x32_bf16 v[56:59], v[168:171], v[198:201], v[56:59]
	v_mfma_f32_16x16x32_bf16 v[44:47], v[160:163], v[206:209], v[44:47]
	v_mfma_f32_16x16x32_bf16 v[40:43], v[168:171], v[206:209], v[40:43]
	v_mfma_f32_16x16x32_bf16 v[28:31], v[160:163], v[214:217], v[28:31]
	v_mfma_f32_16x16x32_bf16 v[24:27], v[168:171], v[214:217], v[24:27]
	v_mfma_f32_16x16x32_bf16 v[12:15], v[160:163], v[222:225], v[12:15]
	v_mfma_f32_16x16x32_bf16 v[8:11], v[168:171], v[222:225], v[8:11]
	s_setprio 0
	s_setprio 1
	v_mfma_f32_16x16x32_bf16 v[52:55], v[172:175], v[194:197], v[52:55]
	v_mfma_f32_16x16x32_bf16 v[48:51], v[184:187], v[194:197], v[48:51]
	v_mfma_f32_16x16x32_bf16 v[36:39], v[172:175], v[202:205], v[36:39]
	v_mfma_f32_16x16x32_bf16 v[32:35], v[184:187], v[202:205], v[32:35]
	v_mfma_f32_16x16x32_bf16 v[20:23], v[172:175], v[210:213], v[20:23]
	v_mfma_f32_16x16x32_bf16 v[16:19], v[184:187], v[210:213], v[16:19]
	v_mfma_f32_16x16x32_bf16 v[4:7], v[172:175], v[218:221], v[4:7]
	v_mfma_f32_16x16x32_bf16 v[0:3], v[184:187], v[218:221], v[0:3]
	v_mfma_f32_16x16x32_bf16 v[52:55], v[176:179], v[198:201], v[52:55]
	v_mfma_f32_16x16x32_bf16 v[48:51], v[190:193], v[198:201], v[48:51]
	v_mfma_f32_16x16x32_bf16 v[36:39], v[176:179], v[206:209], v[36:39]
	v_mfma_f32_16x16x32_bf16 v[32:35], v[190:193], v[206:209], v[32:35]
	v_mfma_f32_16x16x32_bf16 v[20:23], v[176:179], v[214:217], v[20:23]
	v_mfma_f32_16x16x32_bf16 v[16:19], v[190:193], v[214:217], v[16:19]
	v_mfma_f32_16x16x32_bf16 v[4:7], v[176:179], v[222:225], v[4:7]
	v_mfma_f32_16x16x32_bf16 v[0:3], v[190:193], v[222:225], v[0:3]
	s_setprio 0
	s_add_i32 s58, s58, 2
	s_add_u32 s8, s8, 0x100
	s_addc_u32 s9, s9, 0
	s_add_u32 s56, s56, 0x100
	s_addc_u32 s57, s57, 0
	s_cmp_gt_u32 s58, 29
	s_barrier
	s_cbranch_scc0 .LBB0_1114
	s_and_b64 vcc, exec, s[22:23]
	s_cbranch_vccz .LBB0_1117
	s_barrier

.LBB0_2212:
	ds_read_b128 v[140:143], v147
	ds_read_b128 v[154:157], v147 offset:1024
	ds_read_b128 v[158:161], v147 offset:2048
	ds_read_b128 v[162:165], v147 offset:3072
	ds_read_b128 v[166:169], v152
	ds_read_b128 v[170:173], v152 offset:1024
	ds_read_b128 v[174:177], v152 offset:2048
	ds_read_b128 v[178:181], v152 offset:3072
	s_add_u32 s30, s28, 0x100
	s_addc_u32 s31, s29, 0
	s_cmp_eq_u32 s52, 28
	s_cselect_b32 s37, s19, s31
	s_cselect_b32 s36, s25, s30
	s_cselect_b32 s35, s17, s51
	s_cselect_b32 s34, s49, s50
	v_lshl_add_u64 v[216:217], s[28:29], 0, v[132:133]
	s_add_i32 m0, s27, 0xc000
	ds_read_b128 v[184:187], v153
	ds_read_b128 v[188:191], v153 offset:1024
	ds_read_b128 v[192:195], v153 offset:2048
	ds_read_b128 v[196:199], v153 offset:3072
	ds_read_b128 v[200:203], v153 offset:4096
	ds_read_b128 v[204:207], v153 offset:5120
	ds_read_b128 v[208:211], v153 offset:6144
	ds_read_b128 v[212:215], v153 offset:7168
	global_load_lds_dwordx4 v[216:217], off
	v_lshl_add_u64 v[216:217], s[28:29], 0, v[134:135]
	s_add_i32 m0, s27, 0xe000
	s_nop 0
	global_load_lds_dwordx4 v[216:217], off
	s_waitcnt vmcnt(8)
	s_waitcnt lgkmcnt(0)
	s_barrier
	s_setprio 1
	s_waitcnt lgkmcnt(0)
	v_mfma_f32_16x16x32_bf16 v[124:127], v[140:143], v[184:187], v[124:127]
	v_mfma_f32_16x16x32_bf16 v[120:123], v[158:161], v[184:187], v[120:123]
	v_mfma_f32_16x16x32_bf16 v[108:111], v[140:143], v[192:195], v[108:111]
	v_mfma_f32_16x16x32_bf16 v[104:107], v[158:161], v[192:195], v[104:107]
	v_mfma_f32_16x16x32_bf16 v[92:95], v[140:143], v[200:203], v[92:95]
	v_mfma_f32_16x16x32_bf16 v[88:91], v[158:161], v[200:203], v[88:91]
	v_mfma_f32_16x16x32_bf16 v[76:79], v[140:143], v[208:211], v[76:79]
	v_mfma_f32_16x16x32_bf16 v[72:75], v[158:161], v[208:211], v[72:75]
	v_mfma_f32_16x16x32_bf16 v[124:127], v[154:157], v[188:191], v[124:127]
	v_mfma_f32_16x16x32_bf16 v[120:123], v[162:165], v[188:191], v[120:123]
	v_mfma_f32_16x16x32_bf16 v[108:111], v[154:157], v[196:199], v[108:111]
	v_mfma_f32_16x16x32_bf16 v[104:107], v[162:165], v[196:199], v[104:107]
	v_mfma_f32_16x16x32_bf16 v[92:95], v[154:157], v[204:207], v[92:95]
	v_mfma_f32_16x16x32_bf16 v[88:91], v[162:165], v[204:207], v[88:91]
	v_mfma_f32_16x16x32_bf16 v[76:79], v[154:157], v[212:215], v[76:79]
	v_mfma_f32_16x16x32_bf16 v[72:75], v[162:165], v[212:215], v[72:75]
	s_setprio 0
	s_setprio 1
	v_mfma_f32_16x16x32_bf16 v[116:119], v[166:169], v[184:187], v[116:119]
	v_mfma_f32_16x16x32_bf16 v[112:115], v[174:177], v[184:187], v[112:115]
	v_mfma_f32_16x16x32_bf16 v[100:103], v[166:169], v[192:195], v[100:103]
	v_mfma_f32_16x16x32_bf16 v[96:99], v[174:177], v[192:195], v[96:99]
	v_mfma_f32_16x16x32_bf16 v[84:87], v[166:169], v[200:203], v[84:87]
	v_mfma_f32_16x16x32_bf16 v[80:83], v[174:177], v[200:203], v[80:83]
	v_mfma_f32_16x16x32_bf16 v[68:71], v[166:169], v[208:211], v[68:71]
	v_mfma_f32_16x16x32_bf16 v[64:67], v[174:177], v[208:211], v[64:67]
	v_mfma_f32_16x16x32_bf16 v[116:119], v[170:173], v[188:191], v[116:119]
	v_mfma_f32_16x16x32_bf16 v[112:115], v[178:181], v[188:191], v[112:115]
	v_mfma_f32_16x16x32_bf16 v[100:103], v[170:173], v[196:199], v[100:103]
	v_mfma_f32_16x16x32_bf16 v[96:99], v[178:181], v[196:199], v[96:99]
	v_mfma_f32_16x16x32_bf16 v[84:87], v[170:173], v[204:207], v[84:87]
	v_mfma_f32_16x16x32_bf16 v[80:83], v[178:181], v[204:207], v[80:83]
	v_mfma_f32_16x16x32_bf16 v[68:71], v[170:173], v[212:215], v[68:71]
	v_mfma_f32_16x16x32_bf16 v[64:67], v[178:181], v[212:215], v[64:67]
	s_setprio 0
	s_barrier
	s_add_i32 s28, s47, s33
	v_lshl_add_u64 v[216:217], s[34:35], 0, v[128:129]
	s_mov_b32 m0, s28
	ds_read_b128 v[184:187], v153 offset:16384
	ds_read_b128 v[188:191], v153 offset:17408
	ds_read_b128 v[192:195], v153 offset:18432
	ds_read_b128 v[196:199], v153 offset:19456
	ds_read_b128 v[200:203], v153 offset:20480
	ds_read_b128 v[204:207], v153 offset:21504
	ds_read_b128 v[208:211], v153 offset:22528
	ds_read_b128 v[212:215], v153 offset:23552
	global_load_lds_dwordx4 v[216:217], off
	s_add_i32 m0, s28, 0x2000
	s_add_u32 s28, s34, 0x80000
	v_lshl_add_u64 v[218:219], s[34:35], 0, v[130:131]
	s_addc_u32 s29, s35, 0
	s_add_i32 s53, s48, s33
	global_load_lds_dwordx4 v[218:219], off
	v_lshl_add_u64 v[220:221], s[28:29], 0, v[128:129]
	s_mov_b32 m0, s53
	v_lshl_add_u64 v[222:223], s[36:37], 0, v[130:131]
	global_load_lds_dwordx4 v[220:221], off
	v_lshl_add_u64 v[220:221], s[28:29], 0, v[130:131]
	s_add_i32 m0, s53, 0x2000
	s_nop 0
	global_load_lds_dwordx4 v[220:221], off
	v_lshl_add_u64 v[220:221], s[36:37], 0, v[128:129]
	s_mov_b32 m0, s27
	s_nop 0
	global_load_lds_dwordx4 v[220:221], off
	s_mov_b32 m0, s38
	s_nop 0
	global_load_lds_dwordx4 v[222:223], off
	s_waitcnt vmcnt(8)
	s_waitcnt lgkmcnt(0)
	s_barrier
	s_setprio 1
	s_waitcnt lgkmcnt(0)
	v_mfma_f32_16x16x32_bf16 v[60:63], v[140:143], v[184:187], v[60:63]
	v_mfma_f32_16x16x32_bf16 v[56:59], v[158:161], v[184:187], v[56:59]
	v_mfma_f32_16x16x32_bf16 v[44:47], v[140:143], v[192:195], v[44:47]
	v_mfma_f32_16x16x32_bf16 v[40:43], v[158:161], v[192:195], v[40:43]
	v_mfma_f32_16x16x32_bf16 v[28:31], v[140:143], v[200:203], v[28:31]
	v_mfma_f32_16x16x32_bf16 v[24:27], v[158:161], v[200:203], v[24:27]
	v_mfma_f32_16x16x32_bf16 v[12:15], v[140:143], v[208:211], v[12:15]
	v_mfma_f32_16x16x32_bf16 v[8:11], v[158:161], v[208:211], v[8:11]
	v_mfma_f32_16x16x32_bf16 v[60:63], v[154:157], v[188:191], v[60:63]
	v_mfma_f32_16x16x32_bf16 v[56:59], v[162:165], v[188:191], v[56:59]
	v_mfma_f32_16x16x32_bf16 v[44:47], v[154:157], v[196:199], v[44:47]
	v_mfma_f32_16x16x32_bf16 v[40:43], v[162:165], v[196:199], v[40:43]
	v_mfma_f32_16x16x32_bf16 v[28:31], v[154:157], v[204:207], v[28:31]
	v_mfma_f32_16x16x32_bf16 v[24:27], v[162:165], v[204:207], v[24:27]
	v_mfma_f32_16x16x32_bf16 v[12:15], v[154:157], v[212:215], v[12:15]
	v_mfma_f32_16x16x32_bf16 v[8:11], v[162:165], v[212:215], v[8:11]
	s_setprio 0
	s_setprio 1
	v_mfma_f32_16x16x32_bf16 v[52:55], v[166:169], v[184:187], v[52:55]
	v_mfma_f32_16x16x32_bf16 v[48:51], v[174:177], v[184:187], v[48:51]
	v_mfma_f32_16x16x32_bf16 v[36:39], v[166:169], v[192:195], v[36:39]
	v_mfma_f32_16x16x32_bf16 v[32:35], v[174:177], v[192:195], v[32:35]
	v_mfma_f32_16x16x32_bf16 v[20:23], v[166:169], v[200:203], v[20:23]
	v_mfma_f32_16x16x32_bf16 v[16:19], v[174:177], v[200:203], v[16:19]
	v_mfma_f32_16x16x32_bf16 v[4:7], v[166:169], v[208:211], v[4:7]
	v_mfma_f32_16x16x32_bf16 v[0:3], v[174:177], v[208:211], v[0:3]
	v_mfma_f32_16x16x32_bf16 v[52:55], v[170:173], v[188:191], v[52:55]
	v_mfma_f32_16x16x32_bf16 v[48:51], v[178:181], v[188:191], v[48:51]
	v_mfma_f32_16x16x32_bf16 v[36:39], v[170:173], v[196:199], v[36:39]
	v_mfma_f32_16x16x32_bf16 v[32:35], v[178:181], v[196:199], v[32:35]
	v_mfma_f32_16x16x32_bf16 v[20:23], v[170:173], v[204:207], v[20:23]
	v_mfma_f32_16x16x32_bf16 v[16:19], v[178:181], v[204:207], v[16:19]
	v_mfma_f32_16x16x32_bf16 v[4:7], v[170:173], v[212:215], v[4:7]
	v_mfma_f32_16x16x32_bf16 v[0:3], v[178:181], v[212:215], v[0:3]
	s_setprio 0
	s_barrier
	s_add_i32 s53, 0, 0x18000
	s_add_i32 s54, 0, 0x1c000
	v_add_u32_e32 v162, s53, v145
	v_add_u32_e32 v178, s54, v145
	ds_read_b128 v[140:143], v162
	ds_read_b128 v[154:157], v162 offset:1024
	ds_read_b128 v[158:161], v162 offset:2048
	ds_read_b128 v[162:165], v162 offset:3072
	ds_read_b128 v[166:169], v178
	ds_read_b128 v[170:173], v178 offset:1024
	ds_read_b128 v[174:177], v178 offset:2048
	ds_read_b128 v[178:181], v178 offset:3072
	s_add_u32 s28, s36, 0x80000
	s_addc_u32 s29, s37, 0
	s_mov_b32 m0, s39
	v_lshl_add_u64 v[224:225], s[28:29], 0, v[128:129]
	ds_read_b128 v[184:187], v153 offset:32768
	ds_read_b128 v[188:191], v153 offset:33792
	ds_read_b128 v[192:195], v153 offset:34816
	ds_read_b128 v[196:199], v153 offset:35840
	ds_read_b128 v[200:203], v153 offset:36864
	ds_read_b128 v[204:207], v153 offset:37888
	ds_read_b128 v[208:211], v153 offset:38912
	ds_read_b128 v[212:215], v153 offset:39936
	global_load_lds_dwordx4 v[224:225], off
	v_lshl_add_u64 v[224:225], s[28:29], 0, v[130:131]
	s_mov_b32 m0, s40
	s_nop 0
	global_load_lds_dwordx4 v[224:225], off
	s_waitcnt vmcnt(8)
	s_waitcnt lgkmcnt(0)
	s_barrier
	s_setprio 1
	s_waitcnt lgkmcnt(0)
	v_mfma_f32_16x16x32_bf16 v[124:127], v[140:143], v[184:187], v[124:127]
	v_mfma_f32_16x16x32_bf16 v[120:123], v[158:161], v[184:187], v[120:123]
	v_mfma_f32_16x16x32_bf16 v[108:111], v[140:143], v[192:195], v[108:111]
	v_mfma_f32_16x16x32_bf16 v[104:107], v[158:161], v[192:195], v[104:107]
	v_mfma_f32_16x16x32_bf16 v[92:95], v[140:143], v[200:203], v[92:95]
	v_mfma_f32_16x16x32_bf16 v[88:91], v[158:161], v[200:203], v[88:91]
	v_mfma_f32_16x16x32_bf16 v[76:79], v[140:143], v[208:211], v[76:79]
	v_mfma_f32_16x16x32_bf16 v[72:75], v[158:161], v[208:211], v[72:75]
	v_mfma_f32_16x16x32_bf16 v[124:127], v[154:157], v[188:191], v[124:127]
	v_mfma_f32_16x16x32_bf16 v[120:123], v[162:165], v[188:191], v[120:123]
	v_mfma_f32_16x16x32_bf16 v[108:111], v[154:157], v[196:199], v[108:111]
	v_mfma_f32_16x16x32_bf16 v[104:107], v[162:165], v[196:199], v[104:107]
	v_mfma_f32_16x16x32_bf16 v[92:95], v[154:157], v[204:207], v[92:95]
	v_mfma_f32_16x16x32_bf16 v[88:91], v[162:165], v[204:207], v[88:91]
	v_mfma_f32_16x16x32_bf16 v[76:79], v[154:157], v[212:215], v[76:79]
	v_mfma_f32_16x16x32_bf16 v[72:75], v[162:165], v[212:215], v[72:75]
	s_setprio 0
	s_setprio 1
	v_mfma_f32_16x16x32_bf16 v[116:119], v[166:169], v[184:187], v[116:119]
	v_mfma_f32_16x16x32_bf16 v[112:115], v[174:177], v[184:187], v[112:115]
	v_mfma_f32_16x16x32_bf16 v[100:103], v[166:169], v[192:195], v[100:103]
	v_mfma_f32_16x16x32_bf16 v[96:99], v[174:177], v[192:195], v[96:99]
	v_mfma_f32_16x16x32_bf16 v[84:87], v[166:169], v[200:203], v[84:87]
	v_mfma_f32_16x16x32_bf16 v[80:83], v[174:177], v[200:203], v[80:83]
	v_mfma_f32_16x16x32_bf16 v[68:71], v[166:169], v[208:211], v[68:71]
	v_mfma_f32_16x16x32_bf16 v[64:67], v[174:177], v[208:211], v[64:67]
	v_mfma_f32_16x16x32_bf16 v[116:119], v[170:173], v[188:191], v[116:119]
	v_mfma_f32_16x16x32_bf16 v[112:115], v[178:181], v[188:191], v[112:115]
	v_mfma_f32_16x16x32_bf16 v[100:103], v[170:173], v[196:199], v[100:103]
	v_mfma_f32_16x16x32_bf16 v[96:99], v[178:181], v[196:199], v[96:99]
	v_mfma_f32_16x16x32_bf16 v[84:87], v[170:173], v[204:207], v[84:87]
	v_mfma_f32_16x16x32_bf16 v[80:83], v[178:181], v[204:207], v[80:83]
	v_mfma_f32_16x16x32_bf16 v[68:71], v[170:173], v[212:215], v[68:71]
	v_mfma_f32_16x16x32_bf16 v[64:67], v[178:181], v[212:215], v[64:67]
	s_setprio 0
	s_barrier
	s_add_i32 s28, s53, s33
	v_lshl_add_u64 v[216:217], v[216:217], 0, s[12:13]
	s_mov_b32 m0, s28
	ds_read_b128 v[184:187], v153 offset:49152
	ds_read_b128 v[188:191], v153 offset:50176
	ds_read_b128 v[192:195], v153 offset:51200
	ds_read_b128 v[196:199], v153 offset:52224
	ds_read_b128 v[200:203], v153 offset:53248
	ds_read_b128 v[204:207], v153 offset:54272
	ds_read_b128 v[208:211], v153 offset:55296
	ds_read_b128 v[212:215], v153 offset:56320
	global_load_lds_dwordx4 v[216:217], off
	s_add_i32 m0, s28, 0x2000
	s_add_u32 s28, s34, 0x80080
	v_lshl_add_u64 v[216:217], v[218:219], 0, s[12:13]
	s_addc_u32 s29, s35, 0
	s_add_i32 s34, s54, s33
	global_load_lds_dwordx4 v[216:217], off
	v_lshl_add_u64 v[216:217], s[28:29], 0, v[128:129]
	s_mov_b32 m0, s34
	s_nop 0
	global_load_lds_dwordx4 v[216:217], off
	v_lshl_add_u64 v[216:217], s[28:29], 0, v[130:131]
	s_add_i32 m0, s34, 0x2000
	s_nop 0
	global_load_lds_dwordx4 v[216:217], off
	v_lshl_add_u64 v[216:217], v[220:221], 0, s[12:13]
	s_mov_b32 m0, s42
	s_nop 0
	global_load_lds_dwordx4 v[216:217], off
	v_lshl_add_u64 v[216:217], v[222:223], 0, s[12:13]
	s_mov_b32 m0, s43
	s_nop 0
	global_load_lds_dwordx4 v[216:217], off
	s_waitcnt vmcnt(8)
	s_waitcnt lgkmcnt(0)
	s_barrier
	s_setprio 1
	s_waitcnt lgkmcnt(0)
	v_mfma_f32_16x16x32_bf16 v[60:63], v[140:143], v[184:187], v[60:63]
	v_mfma_f32_16x16x32_bf16 v[56:59], v[158:161], v[184:187], v[56:59]
	v_mfma_f32_16x16x32_bf16 v[44:47], v[140:143], v[192:195], v[44:47]
	v_mfma_f32_16x16x32_bf16 v[40:43], v[158:161], v[192:195], v[40:43]
	v_mfma_f32_16x16x32_bf16 v[28:31], v[140:143], v[200:203], v[28:31]
	v_mfma_f32_16x16x32_bf16 v[24:27], v[158:161], v[200:203], v[24:27]
	v_mfma_f32_16x16x32_bf16 v[12:15], v[140:143], v[208:211], v[12:15]
	v_mfma_f32_16x16x32_bf16 v[8:11], v[158:161], v[208:211], v[8:11]
	v_mfma_f32_16x16x32_bf16 v[60:63], v[154:157], v[188:191], v[60:63]
	v_mfma_f32_16x16x32_bf16 v[56:59], v[162:165], v[188:191], v[56:59]
	v_mfma_f32_16x16x32_bf16 v[44:47], v[154:157], v[196:199], v[44:47]
	v_mfma_f32_16x16x32_bf16 v[40:43], v[162:165], v[196:199], v[40:43]
	v_mfma_f32_16x16x32_bf16 v[28:31], v[154:157], v[204:207], v[28:31]
	v_mfma_f32_16x16x32_bf16 v[24:27], v[162:165], v[204:207], v[24:27]
	v_mfma_f32_16x16x32_bf16 v[12:15], v[154:157], v[212:215], v[12:15]
	v_mfma_f32_16x16x32_bf16 v[8:11], v[162:165], v[212:215], v[8:11]
	s_setprio 0
	s_setprio 1
	v_mfma_f32_16x16x32_bf16 v[52:55], v[166:169], v[184:187], v[52:55]
	v_mfma_f32_16x16x32_bf16 v[48:51], v[174:177], v[184:187], v[48:51]
	v_mfma_f32_16x16x32_bf16 v[36:39], v[166:169], v[192:195], v[36:39]
	v_mfma_f32_16x16x32_bf16 v[32:35], v[174:177], v[192:195], v[32:35]
	v_mfma_f32_16x16x32_bf16 v[20:23], v[166:169], v[200:203], v[20:23]
	v_mfma_f32_16x16x32_bf16 v[16:19], v[174:177], v[200:203], v[16:19]
	v_mfma_f32_16x16x32_bf16 v[4:7], v[166:169], v[208:211], v[4:7]
	v_mfma_f32_16x16x32_bf16 v[0:3], v[174:177], v[208:211], v[0:3]
	v_mfma_f32_16x16x32_bf16 v[52:55], v[170:173], v[188:191], v[52:55]
	v_mfma_f32_16x16x32_bf16 v[48:51], v[178:181], v[188:191], v[48:51]
	v_mfma_f32_16x16x32_bf16 v[36:39], v[170:173], v[196:199], v[36:39]
	v_mfma_f32_16x16x32_bf16 v[32:35], v[178:181], v[196:199], v[32:35]
	v_mfma_f32_16x16x32_bf16 v[20:23], v[170:173], v[204:207], v[20:23]
	v_mfma_f32_16x16x32_bf16 v[16:19], v[178:181], v[204:207], v[16:19]
	v_mfma_f32_16x16x32_bf16 v[4:7], v[170:173], v[212:215], v[4:7]
	v_mfma_f32_16x16x32_bf16 v[0:3], v[178:181], v[212:215], v[0:3]
	s_setprio 0
	s_add_i32 s52, s52, 2
	s_add_u32 s50, s50, 0x100
	s_addc_u32 s51, s51, 0
	s_cmp_gt_u32 s52, 29
	s_mov_b64 s[28:29], s[30:31]
	s_barrier
	s_cbranch_scc0 .LBB0_2212
	s_and_b64 vcc, exec, s[14:15]
	s_cbranch_vccz .LBB0_2215
	s_barrier

.LBB0_2311:
	ds_read_b128 v[144:147], v155
	ds_read_b128 v[160:163], v155 offset:1024
	ds_read_b128 v[164:167], v155 offset:2048
	ds_read_b128 v[168:171], v155 offset:3072
	ds_read_b128 v[172:175], v156
	ds_read_b128 v[176:179], v156 offset:1024
	ds_read_b128 v[184:187], v156 offset:2048
	ds_read_b128 v[188:191], v156 offset:3072
	s_add_u32 s22, s20, 0xfff80080
	s_addc_u32 s23, s21, -1
	s_cmp_eq_u32 s48, 28
	s_cselect_b32 s25, s15, s23
	s_cselect_b32 s24, s44, s22
	s_cselect_b32 s23, s13, s47
	s_cselect_b32 s22, s45, s46
	v_lshl_add_u64 v[180:181], s[20:21], 0, v[136:137]
	s_add_i32 m0, s30, 0xc000
	ds_read_b128 v[192:195], v157
	ds_read_b128 v[196:199], v157 offset:1024
	ds_read_b128 v[200:203], v157 offset:2048
	ds_read_b128 v[204:207], v157 offset:3072
	ds_read_b128 v[208:211], v157 offset:4096
	ds_read_b128 v[212:215], v157 offset:5120
	ds_read_b128 v[216:219], v157 offset:6144
	ds_read_b128 v[220:223], v157 offset:7168
	global_load_lds_dwordx4 v[180:181], off
	v_lshl_add_u64 v[180:181], s[20:21], 0, v[138:139]
	s_add_i32 m0, s30, 0xe000
	s_nop 0
	global_load_lds_dwordx4 v[180:181], off
	s_waitcnt vmcnt(8)
	s_waitcnt lgkmcnt(0)
	s_barrier
	s_setprio 1
	s_waitcnt lgkmcnt(0)
	v_mfma_f32_16x16x32_bf16 v[116:119], v[144:147], v[192:195], v[116:119]
	v_mfma_f32_16x16x32_bf16 v[112:115], v[164:167], v[192:195], v[112:115]
	v_mfma_f32_16x16x32_bf16 v[100:103], v[144:147], v[200:203], v[100:103]
	v_mfma_f32_16x16x32_bf16 v[96:99], v[164:167], v[200:203], v[96:99]
	v_mfma_f32_16x16x32_bf16 v[84:87], v[144:147], v[208:211], v[84:87]
	v_mfma_f32_16x16x32_bf16 v[80:83], v[164:167], v[208:211], v[80:83]
	v_mfma_f32_16x16x32_bf16 v[72:75], v[144:147], v[216:219], v[72:75]
	v_mfma_f32_16x16x32_bf16 v[64:67], v[164:167], v[216:219], v[64:67]
	v_mfma_f32_16x16x32_bf16 v[116:119], v[160:163], v[196:199], v[116:119]
	v_mfma_f32_16x16x32_bf16 v[112:115], v[168:171], v[196:199], v[112:115]
	v_mfma_f32_16x16x32_bf16 v[100:103], v[160:163], v[204:207], v[100:103]
	v_mfma_f32_16x16x32_bf16 v[96:99], v[168:171], v[204:207], v[96:99]
	v_mfma_f32_16x16x32_bf16 v[84:87], v[160:163], v[212:215], v[84:87]
	v_mfma_f32_16x16x32_bf16 v[80:83], v[168:171], v[212:215], v[80:83]
	v_mfma_f32_16x16x32_bf16 v[72:75], v[160:163], v[220:223], v[72:75]
	v_mfma_f32_16x16x32_bf16 v[64:67], v[168:171], v[220:223], v[64:67]
	s_setprio 0
	s_setprio 1
	v_mfma_f32_16x16x32_bf16 v[124:127], v[172:175], v[192:195], v[124:127]
	v_mfma_f32_16x16x32_bf16 v[120:123], v[184:187], v[192:195], v[120:123]
	v_mfma_f32_16x16x32_bf16 v[108:111], v[172:175], v[200:203], v[108:111]
	v_mfma_f32_16x16x32_bf16 v[104:107], v[184:187], v[200:203], v[104:107]
	v_mfma_f32_16x16x32_bf16 v[92:95], v[172:175], v[208:211], v[92:95]
	v_mfma_f32_16x16x32_bf16 v[88:91], v[184:187], v[208:211], v[88:91]
	v_mfma_f32_16x16x32_bf16 v[76:79], v[172:175], v[216:219], v[76:79]
	v_mfma_f32_16x16x32_bf16 v[68:71], v[184:187], v[216:219], v[68:71]
	v_mfma_f32_16x16x32_bf16 v[124:127], v[176:179], v[196:199], v[124:127]
	v_mfma_f32_16x16x32_bf16 v[120:123], v[188:191], v[196:199], v[120:123]
	v_mfma_f32_16x16x32_bf16 v[108:111], v[176:179], v[204:207], v[108:111]
	v_mfma_f32_16x16x32_bf16 v[104:107], v[188:191], v[204:207], v[104:107]
	v_mfma_f32_16x16x32_bf16 v[92:95], v[176:179], v[212:215], v[92:95]
	v_mfma_f32_16x16x32_bf16 v[88:91], v[188:191], v[212:215], v[88:91]
	v_mfma_f32_16x16x32_bf16 v[76:79], v[176:179], v[220:223], v[76:79]
	v_mfma_f32_16x16x32_bf16 v[68:71], v[188:191], v[220:223], v[68:71]
	s_setprio 0
	s_barrier
	s_add_i32 s49, s40, s29
	v_lshl_add_u64 v[180:181], s[22:23], 0, v[130:131]
	s_mov_b32 m0, s49
	ds_read_b128 v[192:195], v157 offset:16384
	ds_read_b128 v[196:199], v157 offset:17408
	ds_read_b128 v[200:203], v157 offset:18432
	ds_read_b128 v[204:207], v157 offset:19456
	ds_read_b128 v[208:211], v157 offset:20480
	ds_read_b128 v[212:215], v157 offset:21504
	ds_read_b128 v[216:219], v157 offset:22528
	ds_read_b128 v[220:223], v157 offset:23552
	global_load_lds_dwordx4 v[180:181], off
	s_add_i32 m0, s49, 0x2000
	s_add_u32 s50, s22, 0x80000
	v_lshl_add_u64 v[224:225], s[22:23], 0, v[134:135]
	s_addc_u32 s51, s23, 0
	s_add_i32 s49, s41, s29
	global_load_lds_dwordx4 v[224:225], off
	v_lshl_add_u64 v[226:227], s[50:51], 0, v[130:131]
	s_mov_b32 m0, s49
	v_lshl_add_u64 v[228:229], s[24:25], 0, v[132:133]
	global_load_lds_dwordx4 v[226:227], off
	v_lshl_add_u64 v[226:227], s[50:51], 0, v[134:135]
	s_add_i32 m0, s49, 0x2000
	s_nop 0
	global_load_lds_dwordx4 v[226:227], off
	v_lshl_add_u64 v[226:227], s[24:25], 0, v[128:129]
	s_mov_b32 m0, s30
	s_nop 0
	global_load_lds_dwordx4 v[226:227], off
	s_mov_b32 m0, s31
	s_nop 0
	global_load_lds_dwordx4 v[228:229], off
	s_waitcnt vmcnt(8)
	s_waitcnt lgkmcnt(0)
	s_barrier
	s_setprio 1
	s_waitcnt lgkmcnt(0)
	v_mfma_f32_16x16x32_bf16 v[52:55], v[144:147], v[192:195], v[52:55]
	v_mfma_f32_16x16x32_bf16 v[48:51], v[164:167], v[192:195], v[48:51]
	v_mfma_f32_16x16x32_bf16 v[36:39], v[144:147], v[200:203], v[36:39]
	v_mfma_f32_16x16x32_bf16 v[32:35], v[164:167], v[200:203], v[32:35]
	v_mfma_f32_16x16x32_bf16 v[20:23], v[144:147], v[208:211], v[20:23]
	v_mfma_f32_16x16x32_bf16 v[16:19], v[164:167], v[208:211], v[16:19]
	v_mfma_f32_16x16x32_bf16 v[4:7], v[144:147], v[216:219], v[4:7]
	v_mfma_f32_16x16x32_bf16 v[0:3], v[164:167], v[216:219], v[0:3]
	v_mfma_f32_16x16x32_bf16 v[52:55], v[160:163], v[196:199], v[52:55]
	v_mfma_f32_16x16x32_bf16 v[48:51], v[168:171], v[196:199], v[48:51]
	v_mfma_f32_16x16x32_bf16 v[36:39], v[160:163], v[204:207], v[36:39]
	v_mfma_f32_16x16x32_bf16 v[32:35], v[168:171], v[204:207], v[32:35]
	v_mfma_f32_16x16x32_bf16 v[20:23], v[160:163], v[212:215], v[20:23]
	v_mfma_f32_16x16x32_bf16 v[16:19], v[168:171], v[212:215], v[16:19]
	v_mfma_f32_16x16x32_bf16 v[4:7], v[160:163], v[220:223], v[4:7]
	v_mfma_f32_16x16x32_bf16 v[0:3], v[168:171], v[220:223], v[0:3]
	s_setprio 0
	s_setprio 1
	v_mfma_f32_16x16x32_bf16 v[60:63], v[172:175], v[192:195], v[60:63]
	v_mfma_f32_16x16x32_bf16 v[56:59], v[184:187], v[192:195], v[56:59]
	v_mfma_f32_16x16x32_bf16 v[44:47], v[172:175], v[200:203], v[44:47]
	v_mfma_f32_16x16x32_bf16 v[40:43], v[184:187], v[200:203], v[40:43]
	v_mfma_f32_16x16x32_bf16 v[28:31], v[172:175], v[208:211], v[28:31]
	v_mfma_f32_16x16x32_bf16 v[24:27], v[184:187], v[208:211], v[24:27]
	v_mfma_f32_16x16x32_bf16 v[12:15], v[172:175], v[216:219], v[12:15]
	v_mfma_f32_16x16x32_bf16 v[8:11], v[184:187], v[216:219], v[8:11]
	v_mfma_f32_16x16x32_bf16 v[60:63], v[176:179], v[196:199], v[60:63]
	v_mfma_f32_16x16x32_bf16 v[56:59], v[188:191], v[196:199], v[56:59]
	v_mfma_f32_16x16x32_bf16 v[44:47], v[176:179], v[204:207], v[44:47]
	v_mfma_f32_16x16x32_bf16 v[40:43], v[188:191], v[204:207], v[40:43]
	v_mfma_f32_16x16x32_bf16 v[28:31], v[176:179], v[212:215], v[28:31]
	v_mfma_f32_16x16x32_bf16 v[24:27], v[188:191], v[212:215], v[24:27]
	v_mfma_f32_16x16x32_bf16 v[12:15], v[176:179], v[220:223], v[12:15]
	v_mfma_f32_16x16x32_bf16 v[8:11], v[188:191], v[220:223], v[8:11]
	s_setprio 0
	s_barrier
	s_add_i32 s49, 0, 0x18000
	v_add_u32_e32 v159, s49, v153
	s_add_i32 s50, 0, 0x1c000
	ds_read_b128 v[144:147], v159
	ds_read_b128 v[160:163], v159 offset:1024
	ds_read_b128 v[164:167], v159 offset:2048
	ds_read_b128 v[168:171], v159 offset:3072
	v_add_u32_e32 v159, s50, v153
	ds_read_b128 v[172:175], v159
	ds_read_b128 v[176:179], v159 offset:1024
	ds_read_b128 v[184:187], v159 offset:2048
	ds_read_b128 v[188:191], v159 offset:3072
	s_add_u32 s24, s24, 0x80000
	s_addc_u32 s25, s25, 0
	s_mov_b32 m0, s33
	v_lshl_add_u64 v[230:231], s[24:25], 0, v[128:129]
	ds_read_b128 v[192:195], v157 offset:32768
	ds_read_b128 v[196:199], v157 offset:33792
	ds_read_b128 v[200:203], v157 offset:34816
	ds_read_b128 v[204:207], v157 offset:35840
	ds_read_b128 v[208:211], v157 offset:36864
	ds_read_b128 v[212:215], v157 offset:37888
	ds_read_b128 v[216:219], v157 offset:38912
	ds_read_b128 v[220:223], v157 offset:39936
	global_load_lds_dwordx4 v[230:231], off
	v_lshl_add_u64 v[230:231], s[24:25], 0, v[132:133]
	s_mov_b32 m0, s34
	s_nop 0
	global_load_lds_dwordx4 v[230:231], off
	s_waitcnt vmcnt(8)
	s_waitcnt lgkmcnt(0)
	s_barrier
	s_setprio 1
	s_waitcnt lgkmcnt(0)
	v_mfma_f32_16x16x32_bf16 v[116:119], v[144:147], v[192:195], v[116:119]
	v_mfma_f32_16x16x32_bf16 v[112:115], v[164:167], v[192:195], v[112:115]
	v_mfma_f32_16x16x32_bf16 v[100:103], v[144:147], v[200:203], v[100:103]
	v_mfma_f32_16x16x32_bf16 v[96:99], v[164:167], v[200:203], v[96:99]
	v_mfma_f32_16x16x32_bf16 v[84:87], v[144:147], v[208:211], v[84:87]
	v_mfma_f32_16x16x32_bf16 v[80:83], v[164:167], v[208:211], v[80:83]
	v_mfma_f32_16x16x32_bf16 v[72:75], v[144:147], v[216:219], v[72:75]
	v_mfma_f32_16x16x32_bf16 v[64:67], v[164:167], v[216:219], v[64:67]
	v_mfma_f32_16x16x32_bf16 v[116:119], v[160:163], v[196:199], v[116:119]
	v_mfma_f32_16x16x32_bf16 v[112:115], v[168:171], v[196:199], v[112:115]
	v_mfma_f32_16x16x32_bf16 v[100:103], v[160:163], v[204:207], v[100:103]
	v_mfma_f32_16x16x32_bf16 v[96:99], v[168:171], v[204:207], v[96:99]
	v_mfma_f32_16x16x32_bf16 v[84:87], v[160:163], v[212:215], v[84:87]
	v_mfma_f32_16x16x32_bf16 v[80:83], v[168:171], v[212:215], v[80:83]
	v_mfma_f32_16x16x32_bf16 v[72:75], v[160:163], v[220:223], v[72:75]
	v_mfma_f32_16x16x32_bf16 v[64:67], v[168:171], v[220:223], v[64:67]
	s_setprio 0
	s_setprio 1
	v_mfma_f32_16x16x32_bf16 v[124:127], v[172:175], v[192:195], v[124:127]
	v_mfma_f32_16x16x32_bf16 v[120:123], v[184:187], v[192:195], v[120:123]
	v_mfma_f32_16x16x32_bf16 v[108:111], v[172:175], v[200:203], v[108:111]
	v_mfma_f32_16x16x32_bf16 v[104:107], v[184:187], v[200:203], v[104:107]
	v_mfma_f32_16x16x32_bf16 v[92:95], v[172:175], v[208:211], v[92:95]
	v_mfma_f32_16x16x32_bf16 v[88:91], v[184:187], v[208:211], v[88:91]
	v_mfma_f32_16x16x32_bf16 v[76:79], v[172:175], v[216:219], v[76:79]
	v_mfma_f32_16x16x32_bf16 v[68:71], v[184:187], v[216:219], v[68:71]
	v_mfma_f32_16x16x32_bf16 v[124:127], v[176:179], v[196:199], v[124:127]
	v_mfma_f32_16x16x32_bf16 v[120:123], v[188:191], v[196:199], v[120:123]
	v_mfma_f32_16x16x32_bf16 v[108:111], v[176:179], v[204:207], v[108:111]
	v_mfma_f32_16x16x32_bf16 v[104:107], v[188:191], v[204:207], v[104:107]
	v_mfma_f32_16x16x32_bf16 v[92:95], v[176:179], v[212:215], v[92:95]
	v_mfma_f32_16x16x32_bf16 v[88:91], v[188:191], v[212:215], v[88:91]
	v_mfma_f32_16x16x32_bf16 v[76:79], v[176:179], v[220:223], v[76:79]
	v_mfma_f32_16x16x32_bf16 v[68:71], v[188:191], v[220:223], v[68:71]
	s_setprio 0
	s_barrier
	s_add_i32 s24, s49, s29
	v_lshl_add_u64 v[180:181], v[180:181], 0, s[8:9]
	s_mov_b32 m0, s24
	ds_read_b128 v[192:195], v157 offset:49152
	ds_read_b128 v[196:199], v157 offset:50176
	ds_read_b128 v[200:203], v157 offset:51200
	ds_read_b128 v[204:207], v157 offset:52224
	ds_read_b128 v[208:211], v157 offset:53248
	ds_read_b128 v[212:215], v157 offset:54272
	ds_read_b128 v[216:219], v157 offset:55296
	ds_read_b128 v[220:223], v157 offset:56320
	global_load_lds_dwordx4 v[180:181], off
	s_add_i32 m0, s24, 0x2000
	s_add_u32 s22, s22, 0x80080
	v_lshl_add_u64 v[180:181], v[224:225], 0, s[8:9]
	s_addc_u32 s23, s23, 0
	s_add_i32 s24, s50, s29
	global_load_lds_dwordx4 v[180:181], off
	v_lshl_add_u64 v[180:181], s[22:23], 0, v[130:131]
	s_mov_b32 m0, s24
	s_nop 0
	global_load_lds_dwordx4 v[180:181], off
	v_lshl_add_u64 v[180:181], s[22:23], 0, v[134:135]
	s_add_i32 m0, s24, 0x2000
	s_nop 0
	global_load_lds_dwordx4 v[180:181], off
	v_lshl_add_u64 v[180:181], v[226:227], 0, s[8:9]
	s_mov_b32 m0, s36
	s_nop 0
	global_load_lds_dwordx4 v[180:181], off
	v_lshl_add_u64 v[180:181], v[228:229], 0, s[8:9]
	s_mov_b32 m0, s37
	s_nop 0
	global_load_lds_dwordx4 v[180:181], off
	s_waitcnt vmcnt(8)
	s_waitcnt lgkmcnt(0)
	s_barrier
	s_setprio 1
	s_waitcnt lgkmcnt(0)
	v_mfma_f32_16x16x32_bf16 v[52:55], v[144:147], v[192:195], v[52:55]
	v_mfma_f32_16x16x32_bf16 v[48:51], v[164:167], v[192:195], v[48:51]
	v_mfma_f32_16x16x32_bf16 v[36:39], v[144:147], v[200:203], v[36:39]
	v_mfma_f32_16x16x32_bf16 v[32:35], v[164:167], v[200:203], v[32:35]
	v_mfma_f32_16x16x32_bf16 v[20:23], v[144:147], v[208:211], v[20:23]
	v_mfma_f32_16x16x32_bf16 v[16:19], v[164:167], v[208:211], v[16:19]
	v_mfma_f32_16x16x32_bf16 v[4:7], v[144:147], v[216:219], v[4:7]
	v_mfma_f32_16x16x32_bf16 v[0:3], v[164:167], v[216:219], v[0:3]
	v_mfma_f32_16x16x32_bf16 v[52:55], v[160:163], v[196:199], v[52:55]
	v_mfma_f32_16x16x32_bf16 v[48:51], v[168:171], v[196:199], v[48:51]
	v_mfma_f32_16x16x32_bf16 v[36:39], v[160:163], v[204:207], v[36:39]
	v_mfma_f32_16x16x32_bf16 v[32:35], v[168:171], v[204:207], v[32:35]
	v_mfma_f32_16x16x32_bf16 v[20:23], v[160:163], v[212:215], v[20:23]
	v_mfma_f32_16x16x32_bf16 v[16:19], v[168:171], v[212:215], v[16:19]
	v_mfma_f32_16x16x32_bf16 v[4:7], v[160:163], v[220:223], v[4:7]
	v_mfma_f32_16x16x32_bf16 v[0:3], v[168:171], v[220:223], v[0:3]
	s_setprio 0
	s_setprio 1
	v_mfma_f32_16x16x32_bf16 v[60:63], v[172:175], v[192:195], v[60:63]
	v_mfma_f32_16x16x32_bf16 v[56:59], v[184:187], v[192:195], v[56:59]
	v_mfma_f32_16x16x32_bf16 v[44:47], v[172:175], v[200:203], v[44:47]
	v_mfma_f32_16x16x32_bf16 v[40:43], v[184:187], v[200:203], v[40:43]
	v_mfma_f32_16x16x32_bf16 v[28:31], v[172:175], v[208:211], v[28:31]
	v_mfma_f32_16x16x32_bf16 v[24:27], v[184:187], v[208:211], v[24:27]
	v_mfma_f32_16x16x32_bf16 v[12:15], v[172:175], v[216:219], v[12:15]
	v_mfma_f32_16x16x32_bf16 v[8:11], v[184:187], v[216:219], v[8:11]
	v_mfma_f32_16x16x32_bf16 v[60:63], v[176:179], v[196:199], v[60:63]
	v_mfma_f32_16x16x32_bf16 v[56:59], v[188:191], v[196:199], v[56:59]
	v_mfma_f32_16x16x32_bf16 v[44:47], v[176:179], v[204:207], v[44:47]
	v_mfma_f32_16x16x32_bf16 v[40:43], v[188:191], v[204:207], v[40:43]
	v_mfma_f32_16x16x32_bf16 v[28:31], v[176:179], v[212:215], v[28:31]
	v_mfma_f32_16x16x32_bf16 v[24:27], v[188:191], v[212:215], v[24:27]
	v_mfma_f32_16x16x32_bf16 v[12:15], v[176:179], v[220:223], v[12:15]
	v_mfma_f32_16x16x32_bf16 v[8:11], v[188:191], v[220:223], v[8:11]
	s_setprio 0
	s_add_i32 s48, s48, 2
	s_add_u32 s20, s20, 0x100
	s_addc_u32 s21, s21, 0
	s_add_u32 s46, s46, 0x100
	s_addc_u32 s47, s47, 0
	s_cmp_gt_u32 s48, 29
	s_barrier
	s_cbranch_scc0 .LBB0_2311
	s_and_b64 vcc, exec, s[10:11]
	s_cbranch_vccz .LBB0_2314
	s_barrier

.LBB0_2393:
	ds_read_b128 v[140:143], v147
	ds_read_b128 v[154:157], v147 offset:1024
	ds_read_b128 v[158:161], v147 offset:2048
	ds_read_b128 v[162:165], v147 offset:3072
	ds_read_b128 v[166:169], v152
	ds_read_b128 v[170:173], v152 offset:1024
	ds_read_b128 v[174:177], v152 offset:2048
	ds_read_b128 v[178:181], v152 offset:3072
	s_add_u32 s20, s18, 0x100
	s_addc_u32 s21, s19, 0
	s_cmpk_eq_i32 s46, 0x54
	s_cselect_b32 s25, s1, s21
	s_cselect_b32 s24, s0, s20
	s_cselect_b32 s23, s17, s45
	s_cselect_b32 s22, s16, s44
	v_lshl_add_u64 v[216:217], s[18:19], 0, v[132:133]
	s_add_i32 m0, s27, 0xc000
	ds_read_b128 v[184:187], v153
	ds_read_b128 v[188:191], v153 offset:1024
	ds_read_b128 v[192:195], v153 offset:2048
	ds_read_b128 v[196:199], v153 offset:3072
	ds_read_b128 v[200:203], v153 offset:4096
	ds_read_b128 v[204:207], v153 offset:5120
	ds_read_b128 v[208:211], v153 offset:6144
	ds_read_b128 v[212:215], v153 offset:7168
	global_load_lds_dwordx4 v[216:217], off
	v_lshl_add_u64 v[216:217], s[18:19], 0, v[134:135]
	s_add_i32 m0, s27, 0xe000
	s_nop 0
	global_load_lds_dwordx4 v[216:217], off
	s_waitcnt vmcnt(8)
	s_waitcnt lgkmcnt(0)
	s_barrier
	s_setprio 1
	s_waitcnt lgkmcnt(0)
	v_mfma_f32_16x16x32_bf16 v[124:127], v[140:143], v[184:187], v[124:127]
	v_mfma_f32_16x16x32_bf16 v[120:123], v[158:161], v[184:187], v[120:123]
	v_mfma_f32_16x16x32_bf16 v[108:111], v[140:143], v[192:195], v[108:111]
	v_mfma_f32_16x16x32_bf16 v[104:107], v[158:161], v[192:195], v[104:107]
	v_mfma_f32_16x16x32_bf16 v[92:95], v[140:143], v[200:203], v[92:95]
	v_mfma_f32_16x16x32_bf16 v[88:91], v[158:161], v[200:203], v[88:91]
	v_mfma_f32_16x16x32_bf16 v[76:79], v[140:143], v[208:211], v[76:79]
	v_mfma_f32_16x16x32_bf16 v[72:75], v[158:161], v[208:211], v[72:75]
	v_mfma_f32_16x16x32_bf16 v[124:127], v[154:157], v[188:191], v[124:127]
	v_mfma_f32_16x16x32_bf16 v[120:123], v[162:165], v[188:191], v[120:123]
	v_mfma_f32_16x16x32_bf16 v[108:111], v[154:157], v[196:199], v[108:111]
	v_mfma_f32_16x16x32_bf16 v[104:107], v[162:165], v[196:199], v[104:107]
	v_mfma_f32_16x16x32_bf16 v[92:95], v[154:157], v[204:207], v[92:95]
	v_mfma_f32_16x16x32_bf16 v[88:91], v[162:165], v[204:207], v[88:91]
	v_mfma_f32_16x16x32_bf16 v[76:79], v[154:157], v[212:215], v[76:79]
	v_mfma_f32_16x16x32_bf16 v[72:75], v[162:165], v[212:215], v[72:75]
	s_setprio 0
	s_setprio 1
	v_mfma_f32_16x16x32_bf16 v[116:119], v[166:169], v[184:187], v[116:119]
	v_mfma_f32_16x16x32_bf16 v[112:115], v[174:177], v[184:187], v[112:115]
	v_mfma_f32_16x16x32_bf16 v[100:103], v[166:169], v[192:195], v[100:103]
	v_mfma_f32_16x16x32_bf16 v[96:99], v[174:177], v[192:195], v[96:99]
	v_mfma_f32_16x16x32_bf16 v[84:87], v[166:169], v[200:203], v[84:87]
	v_mfma_f32_16x16x32_bf16 v[80:83], v[174:177], v[200:203], v[80:83]
	v_mfma_f32_16x16x32_bf16 v[68:71], v[166:169], v[208:211], v[68:71]
	v_mfma_f32_16x16x32_bf16 v[64:67], v[174:177], v[208:211], v[64:67]
	v_mfma_f32_16x16x32_bf16 v[116:119], v[170:173], v[188:191], v[116:119]
	v_mfma_f32_16x16x32_bf16 v[112:115], v[178:181], v[188:191], v[112:115]
	v_mfma_f32_16x16x32_bf16 v[100:103], v[170:173], v[196:199], v[100:103]
	v_mfma_f32_16x16x32_bf16 v[96:99], v[178:181], v[196:199], v[96:99]
	v_mfma_f32_16x16x32_bf16 v[84:87], v[170:173], v[204:207], v[84:87]
	v_mfma_f32_16x16x32_bf16 v[80:83], v[178:181], v[204:207], v[80:83]
	v_mfma_f32_16x16x32_bf16 v[68:71], v[170:173], v[212:215], v[68:71]
	v_mfma_f32_16x16x32_bf16 v[64:67], v[178:181], v[212:215], v[64:67]
	s_setprio 0
	s_barrier
	s_add_i32 s18, s38, s26
	v_lshl_add_u64 v[216:217], s[22:23], 0, v[128:129]
	s_mov_b32 m0, s18
	ds_read_b128 v[184:187], v153 offset:16384
	ds_read_b128 v[188:191], v153 offset:17408
	ds_read_b128 v[192:195], v153 offset:18432
	ds_read_b128 v[196:199], v153 offset:19456
	ds_read_b128 v[200:203], v153 offset:20480
	ds_read_b128 v[204:207], v153 offset:21504
	ds_read_b128 v[208:211], v153 offset:22528
	ds_read_b128 v[212:215], v153 offset:23552
	global_load_lds_dwordx4 v[216:217], off
	s_add_i32 m0, s18, 0x2000
	s_add_u32 s18, s22, 0x160000
	v_lshl_add_u64 v[218:219], s[22:23], 0, v[130:131]
	s_addc_u32 s19, s23, 0
	s_add_i32 s47, s39, s26
	global_load_lds_dwordx4 v[218:219], off
	v_lshl_add_u64 v[220:221], s[18:19], 0, v[128:129]
	s_mov_b32 m0, s47
	v_lshl_add_u64 v[222:223], s[24:25], 0, v[130:131]
	global_load_lds_dwordx4 v[220:221], off
	v_lshl_add_u64 v[220:221], s[18:19], 0, v[130:131]
	s_add_i32 m0, s47, 0x2000
	s_nop 0
	global_load_lds_dwordx4 v[220:221], off
	v_lshl_add_u64 v[220:221], s[24:25], 0, v[128:129]
	s_mov_b32 m0, s27
	s_nop 0
	global_load_lds_dwordx4 v[220:221], off
	s_mov_b32 m0, s28
	s_nop 0
	global_load_lds_dwordx4 v[222:223], off
	s_waitcnt vmcnt(8)
	s_waitcnt lgkmcnt(0)
	s_barrier
	s_setprio 1
	s_waitcnt lgkmcnt(0)
	v_mfma_f32_16x16x32_bf16 v[60:63], v[140:143], v[184:187], v[60:63]
	v_mfma_f32_16x16x32_bf16 v[56:59], v[158:161], v[184:187], v[56:59]
	v_mfma_f32_16x16x32_bf16 v[44:47], v[140:143], v[192:195], v[44:47]
	v_mfma_f32_16x16x32_bf16 v[40:43], v[158:161], v[192:195], v[40:43]
	v_mfma_f32_16x16x32_bf16 v[28:31], v[140:143], v[200:203], v[28:31]
	v_mfma_f32_16x16x32_bf16 v[24:27], v[158:161], v[200:203], v[24:27]
	v_mfma_f32_16x16x32_bf16 v[12:15], v[140:143], v[208:211], v[12:15]
	v_mfma_f32_16x16x32_bf16 v[8:11], v[158:161], v[208:211], v[8:11]
	v_mfma_f32_16x16x32_bf16 v[60:63], v[154:157], v[188:191], v[60:63]
	v_mfma_f32_16x16x32_bf16 v[56:59], v[162:165], v[188:191], v[56:59]
	v_mfma_f32_16x16x32_bf16 v[44:47], v[154:157], v[196:199], v[44:47]
	v_mfma_f32_16x16x32_bf16 v[40:43], v[162:165], v[196:199], v[40:43]
	v_mfma_f32_16x16x32_bf16 v[28:31], v[154:157], v[204:207], v[28:31]
	v_mfma_f32_16x16x32_bf16 v[24:27], v[162:165], v[204:207], v[24:27]
	v_mfma_f32_16x16x32_bf16 v[12:15], v[154:157], v[212:215], v[12:15]
	v_mfma_f32_16x16x32_bf16 v[8:11], v[162:165], v[212:215], v[8:11]
	s_setprio 0
	s_setprio 1
	v_mfma_f32_16x16x32_bf16 v[52:55], v[166:169], v[184:187], v[52:55]
	v_mfma_f32_16x16x32_bf16 v[48:51], v[174:177], v[184:187], v[48:51]
	v_mfma_f32_16x16x32_bf16 v[36:39], v[166:169], v[192:195], v[36:39]
	v_mfma_f32_16x16x32_bf16 v[32:35], v[174:177], v[192:195], v[32:35]
	v_mfma_f32_16x16x32_bf16 v[20:23], v[166:169], v[200:203], v[20:23]
	v_mfma_f32_16x16x32_bf16 v[16:19], v[174:177], v[200:203], v[16:19]
	v_mfma_f32_16x16x32_bf16 v[4:7], v[166:169], v[208:211], v[4:7]
	v_mfma_f32_16x16x32_bf16 v[0:3], v[174:177], v[208:211], v[0:3]
	v_mfma_f32_16x16x32_bf16 v[52:55], v[170:173], v[188:191], v[52:55]
	v_mfma_f32_16x16x32_bf16 v[48:51], v[178:181], v[188:191], v[48:51]
	v_mfma_f32_16x16x32_bf16 v[36:39], v[170:173], v[196:199], v[36:39]
	v_mfma_f32_16x16x32_bf16 v[32:35], v[178:181], v[196:199], v[32:35]
	v_mfma_f32_16x16x32_bf16 v[20:23], v[170:173], v[204:207], v[20:23]
	v_mfma_f32_16x16x32_bf16 v[16:19], v[178:181], v[204:207], v[16:19]
	v_mfma_f32_16x16x32_bf16 v[4:7], v[170:173], v[212:215], v[4:7]
	v_mfma_f32_16x16x32_bf16 v[0:3], v[178:181], v[212:215], v[0:3]
	s_setprio 0
	s_barrier
	s_add_i32 s47, 0, 0x18000
	s_add_i32 s48, 0, 0x1c000
	v_add_u32_e32 v162, s47, v145
	v_add_u32_e32 v178, s48, v145
	ds_read_b128 v[140:143], v162
	ds_read_b128 v[154:157], v162 offset:1024
	ds_read_b128 v[158:161], v162 offset:2048
	ds_read_b128 v[162:165], v162 offset:3072
	ds_read_b128 v[166:169], v178
	ds_read_b128 v[170:173], v178 offset:1024
	ds_read_b128 v[174:177], v178 offset:2048
	ds_read_b128 v[178:181], v178 offset:3072
	s_add_u32 s18, s24, 0x160000
	s_addc_u32 s19, s25, 0
	s_mov_b32 m0, s29
	v_lshl_add_u64 v[224:225], s[18:19], 0, v[128:129]
	ds_read_b128 v[184:187], v153 offset:32768
	ds_read_b128 v[188:191], v153 offset:33792
	ds_read_b128 v[192:195], v153 offset:34816
	ds_read_b128 v[196:199], v153 offset:35840
	ds_read_b128 v[200:203], v153 offset:36864
	ds_read_b128 v[204:207], v153 offset:37888
	ds_read_b128 v[208:211], v153 offset:38912
	ds_read_b128 v[212:215], v153 offset:39936
	global_load_lds_dwordx4 v[224:225], off
	v_lshl_add_u64 v[224:225], s[18:19], 0, v[130:131]
	s_mov_b32 m0, s30
	s_nop 0
	global_load_lds_dwordx4 v[224:225], off
	s_waitcnt vmcnt(8)
	s_waitcnt lgkmcnt(0)
	s_barrier
	s_setprio 1
	s_waitcnt lgkmcnt(0)
	v_mfma_f32_16x16x32_bf16 v[124:127], v[140:143], v[184:187], v[124:127]
	v_mfma_f32_16x16x32_bf16 v[120:123], v[158:161], v[184:187], v[120:123]
	v_mfma_f32_16x16x32_bf16 v[108:111], v[140:143], v[192:195], v[108:111]
	v_mfma_f32_16x16x32_bf16 v[104:107], v[158:161], v[192:195], v[104:107]
	v_mfma_f32_16x16x32_bf16 v[92:95], v[140:143], v[200:203], v[92:95]
	v_mfma_f32_16x16x32_bf16 v[88:91], v[158:161], v[200:203], v[88:91]
	v_mfma_f32_16x16x32_bf16 v[76:79], v[140:143], v[208:211], v[76:79]
	v_mfma_f32_16x16x32_bf16 v[72:75], v[158:161], v[208:211], v[72:75]
	v_mfma_f32_16x16x32_bf16 v[124:127], v[154:157], v[188:191], v[124:127]
	v_mfma_f32_16x16x32_bf16 v[120:123], v[162:165], v[188:191], v[120:123]
	v_mfma_f32_16x16x32_bf16 v[108:111], v[154:157], v[196:199], v[108:111]
	v_mfma_f32_16x16x32_bf16 v[104:107], v[162:165], v[196:199], v[104:107]
	v_mfma_f32_16x16x32_bf16 v[92:95], v[154:157], v[204:207], v[92:95]
	v_mfma_f32_16x16x32_bf16 v[88:91], v[162:165], v[204:207], v[88:91]
	v_mfma_f32_16x16x32_bf16 v[76:79], v[154:157], v[212:215], v[76:79]
	v_mfma_f32_16x16x32_bf16 v[72:75], v[162:165], v[212:215], v[72:75]
	s_setprio 0
	s_setprio 1
	v_mfma_f32_16x16x32_bf16 v[116:119], v[166:169], v[184:187], v[116:119]
	v_mfma_f32_16x16x32_bf16 v[112:115], v[174:177], v[184:187], v[112:115]
	v_mfma_f32_16x16x32_bf16 v[100:103], v[166:169], v[192:195], v[100:103]
	v_mfma_f32_16x16x32_bf16 v[96:99], v[174:177], v[192:195], v[96:99]
	v_mfma_f32_16x16x32_bf16 v[84:87], v[166:169], v[200:203], v[84:87]
	v_mfma_f32_16x16x32_bf16 v[80:83], v[174:177], v[200:203], v[80:83]
	v_mfma_f32_16x16x32_bf16 v[68:71], v[166:169], v[208:211], v[68:71]
	v_mfma_f32_16x16x32_bf16 v[64:67], v[174:177], v[208:211], v[64:67]
	v_mfma_f32_16x16x32_bf16 v[116:119], v[170:173], v[188:191], v[116:119]
	v_mfma_f32_16x16x32_bf16 v[112:115], v[178:181], v[188:191], v[112:115]
	v_mfma_f32_16x16x32_bf16 v[100:103], v[170:173], v[196:199], v[100:103]
	v_mfma_f32_16x16x32_bf16 v[96:99], v[178:181], v[196:199], v[96:99]
	v_mfma_f32_16x16x32_bf16 v[84:87], v[170:173], v[204:207], v[84:87]
	v_mfma_f32_16x16x32_bf16 v[80:83], v[178:181], v[204:207], v[80:83]
	v_mfma_f32_16x16x32_bf16 v[68:71], v[170:173], v[212:215], v[68:71]
	v_mfma_f32_16x16x32_bf16 v[64:67], v[178:181], v[212:215], v[64:67]
	s_setprio 0
	s_barrier
	s_add_i32 s18, s47, s26
	v_lshl_add_u64 v[216:217], v[216:217], 0, s[12:13]
	s_mov_b32 m0, s18
	ds_read_b128 v[184:187], v153 offset:49152
	ds_read_b128 v[188:191], v153 offset:50176
	ds_read_b128 v[192:195], v153 offset:51200
	ds_read_b128 v[196:199], v153 offset:52224
	ds_read_b128 v[200:203], v153 offset:53248
	ds_read_b128 v[204:207], v153 offset:54272
	ds_read_b128 v[208:211], v153 offset:55296
	ds_read_b128 v[212:215], v153 offset:56320
	global_load_lds_dwordx4 v[216:217], off
	s_add_i32 m0, s18, 0x2000
	s_add_u32 s18, s22, 0x160080
	v_lshl_add_u64 v[216:217], v[218:219], 0, s[12:13]
	s_addc_u32 s19, s23, 0
	s_add_i32 s22, s48, s26
	global_load_lds_dwordx4 v[216:217], off
	v_lshl_add_u64 v[216:217], s[18:19], 0, v[128:129]
	s_mov_b32 m0, s22
	s_nop 0
	global_load_lds_dwordx4 v[216:217], off
	v_lshl_add_u64 v[216:217], s[18:19], 0, v[130:131]
	s_add_i32 m0, s22, 0x2000
	s_nop 0
	global_load_lds_dwordx4 v[216:217], off
	v_lshl_add_u64 v[216:217], v[220:221], 0, s[12:13]
	s_mov_b32 m0, s33
	s_nop 0
	global_load_lds_dwordx4 v[216:217], off
	v_lshl_add_u64 v[216:217], v[222:223], 0, s[12:13]
	s_mov_b32 m0, s34
	s_nop 0
	global_load_lds_dwordx4 v[216:217], off
	s_waitcnt vmcnt(8)
	s_waitcnt lgkmcnt(0)
	s_barrier
	s_setprio 1
	s_waitcnt lgkmcnt(0)
	v_mfma_f32_16x16x32_bf16 v[60:63], v[140:143], v[184:187], v[60:63]
	v_mfma_f32_16x16x32_bf16 v[56:59], v[158:161], v[184:187], v[56:59]
	v_mfma_f32_16x16x32_bf16 v[44:47], v[140:143], v[192:195], v[44:47]
	v_mfma_f32_16x16x32_bf16 v[40:43], v[158:161], v[192:195], v[40:43]
	v_mfma_f32_16x16x32_bf16 v[28:31], v[140:143], v[200:203], v[28:31]
	v_mfma_f32_16x16x32_bf16 v[24:27], v[158:161], v[200:203], v[24:27]
	v_mfma_f32_16x16x32_bf16 v[12:15], v[140:143], v[208:211], v[12:15]
	v_mfma_f32_16x16x32_bf16 v[8:11], v[158:161], v[208:211], v[8:11]
	v_mfma_f32_16x16x32_bf16 v[60:63], v[154:157], v[188:191], v[60:63]
	v_mfma_f32_16x16x32_bf16 v[56:59], v[162:165], v[188:191], v[56:59]
	v_mfma_f32_16x16x32_bf16 v[44:47], v[154:157], v[196:199], v[44:47]
	v_mfma_f32_16x16x32_bf16 v[40:43], v[162:165], v[196:199], v[40:43]
	v_mfma_f32_16x16x32_bf16 v[28:31], v[154:157], v[204:207], v[28:31]
	v_mfma_f32_16x16x32_bf16 v[24:27], v[162:165], v[204:207], v[24:27]
	v_mfma_f32_16x16x32_bf16 v[12:15], v[154:157], v[212:215], v[12:15]
	v_mfma_f32_16x16x32_bf16 v[8:11], v[162:165], v[212:215], v[8:11]
	s_setprio 0
	s_setprio 1
	v_mfma_f32_16x16x32_bf16 v[52:55], v[166:169], v[184:187], v[52:55]
	v_mfma_f32_16x16x32_bf16 v[48:51], v[174:177], v[184:187], v[48:51]
	v_mfma_f32_16x16x32_bf16 v[36:39], v[166:169], v[192:195], v[36:39]
	v_mfma_f32_16x16x32_bf16 v[32:35], v[174:177], v[192:195], v[32:35]
	v_mfma_f32_16x16x32_bf16 v[20:23], v[166:169], v[200:203], v[20:23]
	v_mfma_f32_16x16x32_bf16 v[16:19], v[174:177], v[200:203], v[16:19]
	v_mfma_f32_16x16x32_bf16 v[4:7], v[166:169], v[208:211], v[4:7]
	v_mfma_f32_16x16x32_bf16 v[0:3], v[174:177], v[208:211], v[0:3]
	v_mfma_f32_16x16x32_bf16 v[52:55], v[170:173], v[188:191], v[52:55]
	v_mfma_f32_16x16x32_bf16 v[48:51], v[178:181], v[188:191], v[48:51]
	v_mfma_f32_16x16x32_bf16 v[36:39], v[170:173], v[196:199], v[36:39]
	v_mfma_f32_16x16x32_bf16 v[32:35], v[178:181], v[196:199], v[32:35]
	v_mfma_f32_16x16x32_bf16 v[20:23], v[170:173], v[204:207], v[20:23]
	v_mfma_f32_16x16x32_bf16 v[16:19], v[178:181], v[204:207], v[16:19]
	v_mfma_f32_16x16x32_bf16 v[4:7], v[170:173], v[212:215], v[4:7]
	v_mfma_f32_16x16x32_bf16 v[0:3], v[178:181], v[212:215], v[0:3]
	s_setprio 0
	s_add_i32 s46, s46, 2
	s_add_u32 s44, s44, 0x100
	s_addc_u32 s45, s45, 0
	s_cmpk_gt_u32 s46, 0x55
	s_mov_b64 s[18:19], s[20:21]
	s_barrier
	s_cbranch_scc0 .LBB0_2393
	s_and_b64 vcc, exec, s[14:15]
	s_cbranch_vccz .LBB0_2396
	s_barrier
